# v11 + K-loops: s_setprio 1 raised before the MFMA block's opening barrier
# speedup vs baseline: 1.0093x; 1.0093x over previous
.LBB0_439:
	ds_read_b128 v[128:131], v192
	ds_read_b128 v[132:135], v192 offset:1024
	ds_read_b128 v[136:139], v192 offset:2048
	ds_read_b128 v[158:161], v192 offset:3072
	ds_read_b128 v[168:171], v193
	ds_read_b128 v[172:175], v193 offset:1024
	ds_read_b128 v[196:199], v193 offset:2048
	ds_read_b128 v[200:203], v193 offset:3072
	s_add_u32 s66, s64, 0xfffc0080
	s_addc_u32 s67, s65, -1
	s_cmp_eq_u32 s86, 12
	s_cselect_b32 s69, s53, s67
	s_cselect_b32 s68, s57, s66
	s_cselect_b32 s67, s55, s85
	s_cselect_b32 s66, s63, s84
	s_cselect_b32 s98, 1, 0
	v_lshl_add_u64 v[162:163], s[64:65], 0, v[150:151]
	s_add_i32 m0, s70, 0xc000
	ds_read_b128 v[204:207], v194
	ds_read_b128 v[208:211], v194 offset:1024
	ds_read_b128 v[212:215], v194 offset:2048
	ds_read_b128 v[216:219], v194 offset:3072
	ds_read_b128 v[220:223], v194 offset:4096
	ds_read_b128 v[224:227], v194 offset:5120
	ds_read_b128 v[228:231], v194 offset:6144
	ds_read_b128 v[232:235], v194 offset:7168
	global_load_lds_dwordx4 v[162:163], off
	v_lshl_add_u64 v[162:163], s[64:65], 0, v[152:153]
	s_add_i32 m0, s70, 0xe000
	s_nop 0
	global_load_lds_dwordx4 v[162:163], off
	s_waitcnt vmcnt(8)
	s_waitcnt lgkmcnt(0)
	s_setprio 1
	s_cmp_lg_u32 s98, 0
	s_cbranch_scc0 .Lg1_nopf
	s_lshl_b32 s99, s52, 8
	v_add_u32_e32 v240, s99, v165
	v_ashrrev_i32_e32 v241, 31, v240
	v_lshl_add_u64 v[240:241], v[240:241], 2, s[20:21]
	global_load_dword v242, v[240:241], off
	global_load_dword v243, v[240:241], off offset:64
	global_load_dword v244, v[240:241], off offset:128
	global_load_dword v245, v[240:241], off offset:192
	global_load_dword v246, v[240:241], off offset:512
	global_load_dword v248, v[240:241], off offset:576
	global_load_dword v249, v[240:241], off offset:640
	global_load_dword v250, v[240:241], off offset:704
.Lg1_nopf:
	s_barrier
	v_mfma_f32_16x16x32_bf16 v[124:127], v[128:131], v[204:207], v[124:127]
	v_mfma_f32_16x16x32_bf16 v[120:123], v[136:139], v[204:207], v[120:123]
	v_mfma_f32_16x16x32_bf16 v[96:99], v[128:131], v[212:215], v[96:99]
	v_mfma_f32_16x16x32_bf16 v[88:91], v[136:139], v[212:215], v[88:91]
	v_mfma_f32_16x16x32_bf16 v[76:79], v[128:131], v[220:223], v[76:79]
	v_mfma_f32_16x16x32_bf16 v[72:75], v[136:139], v[220:223], v[72:75]
	v_mfma_f32_16x16x32_bf16 v[60:63], v[128:131], v[228:231], v[60:63]
	v_mfma_f32_16x16x32_bf16 v[108:111], v[136:139], v[228:231], v[108:111]
	v_mfma_f32_16x16x32_bf16 v[124:127], v[132:135], v[208:211], v[124:127]
	v_mfma_f32_16x16x32_bf16 v[120:123], v[158:161], v[208:211], v[120:123]
	v_mfma_f32_16x16x32_bf16 v[96:99], v[132:135], v[216:219], v[96:99]
	v_mfma_f32_16x16x32_bf16 v[88:91], v[158:161], v[216:219], v[88:91]
	v_mfma_f32_16x16x32_bf16 v[76:79], v[132:135], v[224:227], v[76:79]
	v_mfma_f32_16x16x32_bf16 v[72:75], v[158:161], v[224:227], v[72:75]
	v_mfma_f32_16x16x32_bf16 v[60:63], v[132:135], v[232:235], v[60:63]
	v_mfma_f32_16x16x32_bf16 v[108:111], v[158:161], v[232:235], v[108:111]
	s_setprio 0
	s_setprio 1
	v_mfma_f32_16x16x32_bf16 v[116:119], v[168:171], v[204:207], v[116:119]
	v_mfma_f32_16x16x32_bf16 v[112:115], v[196:199], v[204:207], v[112:115]
	v_mfma_f32_16x16x32_bf16 v[84:87], v[168:171], v[212:215], v[84:87]
	v_mfma_f32_16x16x32_bf16 v[80:83], v[196:199], v[212:215], v[80:83]
	v_mfma_f32_16x16x32_bf16 v[68:71], v[168:171], v[220:223], v[68:71]
	v_mfma_f32_16x16x32_bf16 v[64:67], v[196:199], v[220:223], v[64:67]
	v_mfma_f32_16x16x32_bf16 v[104:107], v[168:171], v[228:231], v[104:107]
	v_mfma_f32_16x16x32_bf16 v[56:59], v[196:199], v[228:231], v[56:59]
	v_mfma_f32_16x16x32_bf16 v[116:119], v[172:175], v[208:211], v[116:119]
	v_mfma_f32_16x16x32_bf16 v[112:115], v[200:203], v[208:211], v[112:115]
	v_mfma_f32_16x16x32_bf16 v[84:87], v[172:175], v[216:219], v[84:87]
	v_mfma_f32_16x16x32_bf16 v[80:83], v[200:203], v[216:219], v[80:83]
	v_mfma_f32_16x16x32_bf16 v[68:71], v[172:175], v[224:227], v[68:71]
	v_mfma_f32_16x16x32_bf16 v[64:67], v[200:203], v[224:227], v[64:67]
	v_mfma_f32_16x16x32_bf16 v[104:107], v[172:175], v[232:235], v[104:107]
	v_mfma_f32_16x16x32_bf16 v[56:59], v[200:203], v[232:235], v[56:59]
	s_setprio 0
	s_barrier
	s_add_i32 s87, s82, s23
	v_lshl_add_u64 v[162:163], s[66:67], 0, v[140:141]
	s_mov_b32 m0, s87
	ds_read_b128 v[204:207], v194 offset:16384
	ds_read_b128 v[208:211], v194 offset:17408
	ds_read_b128 v[212:215], v194 offset:18432
	ds_read_b128 v[216:219], v194 offset:19456
	ds_read_b128 v[220:223], v194 offset:20480
	ds_read_b128 v[224:227], v194 offset:21504
	ds_read_b128 v[228:231], v194 offset:22528
	ds_read_b128 v[232:235], v194 offset:23552
	global_load_lds_dwordx4 v[162:163], off
	s_add_i32 m0, s87, 0x2000
	s_add_u32 s88, s66, 0x40000
	v_lshl_add_u64 v[178:179], s[66:67], 0, v[142:143]
	s_addc_u32 s89, s67, 0
	s_add_i32 s87, s83, s23
	global_load_lds_dwordx4 v[178:179], off
	v_lshl_add_u64 v[184:185], s[88:89], 0, v[140:141]
	s_mov_b32 m0, s87
	v_lshl_add_u64 v[236:237], s[68:69], 0, v[142:143]
	global_load_lds_dwordx4 v[184:185], off
	v_lshl_add_u64 v[184:185], s[88:89], 0, v[142:143]
	s_add_i32 m0, s87, 0x2000
	s_nop 0
	global_load_lds_dwordx4 v[184:185], off
	v_lshl_add_u64 v[184:185], s[68:69], 0, v[140:141]
	s_mov_b32 m0, s70
	s_nop 0
	global_load_lds_dwordx4 v[184:185], off
	s_mov_b32 m0, s71
	s_nop 0
	global_load_lds_dwordx4 v[236:237], off
	s_waitcnt vmcnt(8)
	s_waitcnt lgkmcnt(0)
	s_setprio 1
	s_barrier
	v_mfma_f32_16x16x32_bf16 v[52:55], v[128:131], v[204:207], v[52:55]
	v_mfma_f32_16x16x32_bf16 v[48:51], v[136:139], v[204:207], v[48:51]
	v_mfma_f32_16x16x32_bf16 v[16:19], v[128:131], v[212:215], v[16:19]
	v_mfma_f32_16x16x32_bf16 v[8:11], v[136:139], v[212:215], v[8:11]
	v_mfma_f32_16x16x32_bf16 v[28:31], v[128:131], v[220:223], v[28:31]
	v_mfma_f32_16x16x32_bf16 v[24:27], v[136:139], v[220:223], v[24:27]
	v_mfma_f32_16x16x32_bf16 v[36:39], v[128:131], v[228:231], v[36:39]
	v_mfma_f32_16x16x32_bf16 v[100:103], v[136:139], v[228:231], v[100:103]
	v_mfma_f32_16x16x32_bf16 v[52:55], v[132:135], v[208:211], v[52:55]
	v_mfma_f32_16x16x32_bf16 v[48:51], v[158:161], v[208:211], v[48:51]
	v_mfma_f32_16x16x32_bf16 v[16:19], v[132:135], v[216:219], v[16:19]
	v_mfma_f32_16x16x32_bf16 v[8:11], v[158:161], v[216:219], v[8:11]
	v_mfma_f32_16x16x32_bf16 v[28:31], v[132:135], v[224:227], v[28:31]
	v_mfma_f32_16x16x32_bf16 v[24:27], v[158:161], v[224:227], v[24:27]
	v_mfma_f32_16x16x32_bf16 v[36:39], v[132:135], v[232:235], v[36:39]
	v_mfma_f32_16x16x32_bf16 v[100:103], v[158:161], v[232:235], v[100:103]
	s_setprio 0
	s_setprio 1
	v_mfma_f32_16x16x32_bf16 v[44:47], v[168:171], v[204:207], v[44:47]
	v_mfma_f32_16x16x32_bf16 v[40:43], v[196:199], v[204:207], v[40:43]
	v_mfma_f32_16x16x32_bf16 v[0:3], v[168:171], v[212:215], v[0:3]
	v_mfma_f32_16x16x32_bf16 v[4:7], v[196:199], v[212:215], v[4:7]
	v_mfma_f32_16x16x32_bf16 v[12:15], v[168:171], v[220:223], v[12:15]
	v_mfma_f32_16x16x32_bf16 v[20:23], v[196:199], v[220:223], v[20:23]
	v_mfma_f32_16x16x32_bf16 v[92:95], v[168:171], v[228:231], v[92:95]
	v_mfma_f32_16x16x32_bf16 v[32:35], v[196:199], v[228:231], v[32:35]
	v_mfma_f32_16x16x32_bf16 v[44:47], v[172:175], v[208:211], v[44:47]
	v_mfma_f32_16x16x32_bf16 v[40:43], v[200:203], v[208:211], v[40:43]
	v_mfma_f32_16x16x32_bf16 v[0:3], v[172:175], v[216:219], v[0:3]
	v_mfma_f32_16x16x32_bf16 v[4:7], v[200:203], v[216:219], v[4:7]
	v_mfma_f32_16x16x32_bf16 v[12:15], v[172:175], v[224:227], v[12:15]
	v_mfma_f32_16x16x32_bf16 v[20:23], v[200:203], v[224:227], v[20:23]
	v_mfma_f32_16x16x32_bf16 v[92:95], v[172:175], v[232:235], v[92:95]
	v_mfma_f32_16x16x32_bf16 v[32:35], v[200:203], v[232:235], v[32:35]
	s_setprio 0
	s_barrier
	s_add_i32 s87, 0, 0x18000
	s_add_i32 s88, 0, 0x1c000
	v_add_u32_e32 v158, s87, v167
	v_add_u32_e32 v164, s88, v167
	ds_read_b128 v[128:131], v158
	ds_read_b128 v[132:135], v158 offset:1024
	ds_read_b128 v[136:139], v158 offset:2048
	ds_read_b128 v[158:161], v158 offset:3072
	ds_read_b128 v[168:171], v164
	ds_read_b128 v[172:175], v164 offset:1024
	ds_read_b128 v[196:199], v164 offset:2048
	ds_read_b128 v[200:203], v164 offset:3072
	s_add_u32 s68, s68, 0x40000
	s_addc_u32 s69, s69, 0
	s_mov_b32 m0, s72
	v_lshl_add_u64 v[238:239], s[68:69], 0, v[140:141]
	ds_read_b128 v[204:207], v194 offset:32768
	ds_read_b128 v[208:211], v194 offset:33792
	ds_read_b128 v[212:215], v194 offset:34816
	ds_read_b128 v[216:219], v194 offset:35840
	ds_read_b128 v[220:223], v194 offset:36864
	ds_read_b128 v[224:227], v194 offset:37888
	ds_read_b128 v[228:231], v194 offset:38912
	ds_read_b128 v[232:235], v194 offset:39936
	global_load_lds_dwordx4 v[238:239], off
	v_lshl_add_u64 v[238:239], s[68:69], 0, v[142:143]
	s_mov_b32 m0, s73
	s_nop 0
	global_load_lds_dwordx4 v[238:239], off
	s_waitcnt vmcnt(8)
	s_waitcnt lgkmcnt(0)
	s_setprio 1
	s_barrier
	v_mfma_f32_16x16x32_bf16 v[124:127], v[128:131], v[204:207], v[124:127]
	v_mfma_f32_16x16x32_bf16 v[120:123], v[136:139], v[204:207], v[120:123]
	v_mfma_f32_16x16x32_bf16 v[96:99], v[128:131], v[212:215], v[96:99]
	v_mfma_f32_16x16x32_bf16 v[88:91], v[136:139], v[212:215], v[88:91]
	v_mfma_f32_16x16x32_bf16 v[76:79], v[128:131], v[220:223], v[76:79]
	v_mfma_f32_16x16x32_bf16 v[72:75], v[136:139], v[220:223], v[72:75]
	v_mfma_f32_16x16x32_bf16 v[60:63], v[128:131], v[228:231], v[60:63]
	v_mfma_f32_16x16x32_bf16 v[108:111], v[136:139], v[228:231], v[108:111]
	v_mfma_f32_16x16x32_bf16 v[124:127], v[132:135], v[208:211], v[124:127]
	v_mfma_f32_16x16x32_bf16 v[120:123], v[158:161], v[208:211], v[120:123]
	v_mfma_f32_16x16x32_bf16 v[96:99], v[132:135], v[216:219], v[96:99]
	v_mfma_f32_16x16x32_bf16 v[88:91], v[158:161], v[216:219], v[88:91]
	v_mfma_f32_16x16x32_bf16 v[76:79], v[132:135], v[224:227], v[76:79]
	v_mfma_f32_16x16x32_bf16 v[72:75], v[158:161], v[224:227], v[72:75]
	v_mfma_f32_16x16x32_bf16 v[60:63], v[132:135], v[232:235], v[60:63]
	v_mfma_f32_16x16x32_bf16 v[108:111], v[158:161], v[232:235], v[108:111]
	s_setprio 0
	s_setprio 1
	v_mfma_f32_16x16x32_bf16 v[116:119], v[168:171], v[204:207], v[116:119]
	v_mfma_f32_16x16x32_bf16 v[112:115], v[196:199], v[204:207], v[112:115]
	v_mfma_f32_16x16x32_bf16 v[84:87], v[168:171], v[212:215], v[84:87]
	v_mfma_f32_16x16x32_bf16 v[80:83], v[196:199], v[212:215], v[80:83]
	v_mfma_f32_16x16x32_bf16 v[68:71], v[168:171], v[220:223], v[68:71]
	v_mfma_f32_16x16x32_bf16 v[64:67], v[196:199], v[220:223], v[64:67]
	v_mfma_f32_16x16x32_bf16 v[104:107], v[168:171], v[228:231], v[104:107]
	v_mfma_f32_16x16x32_bf16 v[56:59], v[196:199], v[228:231], v[56:59]
	v_mfma_f32_16x16x32_bf16 v[116:119], v[172:175], v[208:211], v[116:119]
	v_mfma_f32_16x16x32_bf16 v[112:115], v[200:203], v[208:211], v[112:115]
	v_mfma_f32_16x16x32_bf16 v[84:87], v[172:175], v[216:219], v[84:87]
	v_mfma_f32_16x16x32_bf16 v[80:83], v[200:203], v[216:219], v[80:83]
	v_mfma_f32_16x16x32_bf16 v[68:71], v[172:175], v[224:227], v[68:71]
	v_mfma_f32_16x16x32_bf16 v[64:67], v[200:203], v[224:227], v[64:67]
	v_mfma_f32_16x16x32_bf16 v[104:107], v[172:175], v[232:235], v[104:107]
	v_mfma_f32_16x16x32_bf16 v[56:59], v[200:203], v[232:235], v[56:59]
	s_setprio 0
	s_barrier
	s_add_i32 s68, s87, s23
	v_lshl_add_u64 v[162:163], v[162:163], 0, s[36:37]
	s_mov_b32 m0, s68
	ds_read_b128 v[204:207], v194 offset:49152
	ds_read_b128 v[208:211], v194 offset:50176
	ds_read_b128 v[212:215], v194 offset:51200
	ds_read_b128 v[216:219], v194 offset:52224
	ds_read_b128 v[220:223], v194 offset:53248
	ds_read_b128 v[224:227], v194 offset:54272
	ds_read_b128 v[228:231], v194 offset:55296
	ds_read_b128 v[232:235], v194 offset:56320
	global_load_lds_dwordx4 v[162:163], off
	s_add_i32 m0, s68, 0x2000
	s_add_u32 s66, s66, 0x40080
	v_lshl_add_u64 v[162:163], v[178:179], 0, s[36:37]
	s_addc_u32 s67, s67, 0
	s_add_i32 s68, s88, s23
	global_load_lds_dwordx4 v[162:163], off
	v_lshl_add_u64 v[162:163], s[66:67], 0, v[140:141]
	s_mov_b32 m0, s68
	s_nop 0
	global_load_lds_dwordx4 v[162:163], off
	v_lshl_add_u64 v[162:163], s[66:67], 0, v[142:143]
	s_add_i32 m0, s68, 0x2000
	s_nop 0
	global_load_lds_dwordx4 v[162:163], off
	v_lshl_add_u64 v[162:163], v[184:185], 0, s[36:37]
	s_mov_b32 m0, s80
	s_nop 0
	global_load_lds_dwordx4 v[162:163], off
	v_lshl_add_u64 v[162:163], v[236:237], 0, s[36:37]
	s_mov_b32 m0, s81
	s_nop 0
	global_load_lds_dwordx4 v[162:163], off
	s_waitcnt vmcnt(8)
	s_waitcnt lgkmcnt(0)
	s_setprio 1
	s_barrier
	v_mfma_f32_16x16x32_bf16 v[52:55], v[128:131], v[204:207], v[52:55]
	v_mfma_f32_16x16x32_bf16 v[48:51], v[136:139], v[204:207], v[48:51]
	v_mfma_f32_16x16x32_bf16 v[16:19], v[128:131], v[212:215], v[16:19]
	v_mfma_f32_16x16x32_bf16 v[8:11], v[136:139], v[212:215], v[8:11]
	v_mfma_f32_16x16x32_bf16 v[28:31], v[128:131], v[220:223], v[28:31]
	v_mfma_f32_16x16x32_bf16 v[24:27], v[136:139], v[220:223], v[24:27]
	v_mfma_f32_16x16x32_bf16 v[36:39], v[128:131], v[228:231], v[36:39]
	v_mfma_f32_16x16x32_bf16 v[100:103], v[136:139], v[228:231], v[100:103]
	v_mfma_f32_16x16x32_bf16 v[52:55], v[132:135], v[208:211], v[52:55]
	v_mfma_f32_16x16x32_bf16 v[48:51], v[158:161], v[208:211], v[48:51]
	v_mfma_f32_16x16x32_bf16 v[16:19], v[132:135], v[216:219], v[16:19]
	v_mfma_f32_16x16x32_bf16 v[8:11], v[158:161], v[216:219], v[8:11]
	v_mfma_f32_16x16x32_bf16 v[28:31], v[132:135], v[224:227], v[28:31]
	v_mfma_f32_16x16x32_bf16 v[24:27], v[158:161], v[224:227], v[24:27]
	v_mfma_f32_16x16x32_bf16 v[36:39], v[132:135], v[232:235], v[36:39]
	v_mfma_f32_16x16x32_bf16 v[100:103], v[158:161], v[232:235], v[100:103]
	s_setprio 0
	s_setprio 1
	v_mfma_f32_16x16x32_bf16 v[44:47], v[168:171], v[204:207], v[44:47]
	v_mfma_f32_16x16x32_bf16 v[40:43], v[196:199], v[204:207], v[40:43]
	v_mfma_f32_16x16x32_bf16 v[0:3], v[168:171], v[212:215], v[0:3]
	v_mfma_f32_16x16x32_bf16 v[4:7], v[196:199], v[212:215], v[4:7]
	v_mfma_f32_16x16x32_bf16 v[12:15], v[168:171], v[220:223], v[12:15]
	v_mfma_f32_16x16x32_bf16 v[20:23], v[196:199], v[220:223], v[20:23]
	v_mfma_f32_16x16x32_bf16 v[92:95], v[168:171], v[228:231], v[92:95]
	v_mfma_f32_16x16x32_bf16 v[32:35], v[196:199], v[228:231], v[32:35]
	v_mfma_f32_16x16x32_bf16 v[44:47], v[172:175], v[208:211], v[44:47]
	v_mfma_f32_16x16x32_bf16 v[40:43], v[200:203], v[208:211], v[40:43]
	v_mfma_f32_16x16x32_bf16 v[0:3], v[172:175], v[216:219], v[0:3]
	v_mfma_f32_16x16x32_bf16 v[4:7], v[200:203], v[216:219], v[4:7]
	v_mfma_f32_16x16x32_bf16 v[12:15], v[172:175], v[224:227], v[12:15]
	v_mfma_f32_16x16x32_bf16 v[20:23], v[200:203], v[224:227], v[20:23]
	v_mfma_f32_16x16x32_bf16 v[92:95], v[172:175], v[232:235], v[92:95]
	v_mfma_f32_16x16x32_bf16 v[32:35], v[200:203], v[232:235], v[32:35]
	s_setprio 0
	s_barrier
	s_add_i32 s86, s86, 2
	s_add_u32 s64, s64, 0x100
	s_addc_u32 s65, s65, 0
	s_add_u32 s84, s84, 0x100
	s_addc_u32 s85, s85, 0
	s_cmp_gt_u32 s86, 13
	s_cbranch_scc0 .LBB0_439
	s_and_b64 vcc, exec, s[38:39]
	s_cbranch_vccz .LBB0_442
	s_barrier

.LBB0_504:
	ds_read_b128 v[104:107], v200
	ds_read_b128 v[108:111], v200 offset:1024
	ds_read_b128 v[124:127], v200 offset:2048
	ds_read_b128 v[128:131], v200 offset:3072
	ds_read_b128 v[144:147], v201
	ds_read_b128 v[148:151], v201 offset:1024
	ds_read_b128 v[152:155], v201 offset:2048
	ds_read_b128 v[156:159], v201 offset:3072
	s_add_u32 s48, s46, 0xfffc0080
	s_addc_u32 s49, s47, -1
	s_cmp_eq_u32 s87, 12
	s_cselect_b32 s51, s39, s49
	s_cselect_b32 s50, s45, s48
	s_cselect_b32 s49, s37, s86
	s_cselect_b32 s48, s84, s85
	v_lshl_add_u64 v[196:197], s[46:47], 0, v[188:189]
	s_add_i32 m0, s52, 0xc000
	ds_read_b128 v[160:163], v202
	ds_read_b128 v[164:167], v202 offset:1024
	ds_read_b128 v[168:171], v202 offset:2048
	ds_read_b128 v[172:175], v202 offset:3072
	ds_read_b128 v[176:179], v202 offset:4096
	ds_read_b128 v[180:183], v202 offset:5120
	ds_read_b128 v[206:209], v202 offset:6144
	ds_read_b128 v[210:213], v202 offset:7168
	global_load_lds_dwordx4 v[196:197], off
	v_lshl_add_u64 v[196:197], s[46:47], 0, v[190:191]
	s_add_i32 m0, s52, 0xe000
	s_nop 0
	global_load_lds_dwordx4 v[196:197], off
	s_waitcnt vmcnt(8)
	s_waitcnt lgkmcnt(0)
	s_setprio 1
	s_barrier
	v_mfma_f32_16x16x32_bf16 v[140:143], v[104:107], v[160:163], v[140:143]
	v_mfma_f32_16x16x32_bf16 v[136:139], v[124:127], v[160:163], v[136:139]
	v_mfma_f32_16x16x32_bf16 v[116:119], v[104:107], v[168:171], v[116:119]
	v_mfma_f32_16x16x32_bf16 v[112:115], v[124:127], v[168:171], v[112:115]
	v_mfma_f32_16x16x32_bf16 v[92:95], v[104:107], v[176:179], v[92:95]
	v_mfma_f32_16x16x32_bf16 v[88:91], v[124:127], v[176:179], v[88:91]
	v_mfma_f32_16x16x32_bf16 v[76:79], v[104:107], v[206:209], v[76:79]
	v_mfma_f32_16x16x32_bf16 v[72:75], v[124:127], v[206:209], v[72:75]
	v_mfma_f32_16x16x32_bf16 v[140:143], v[108:111], v[164:167], v[140:143]
	v_mfma_f32_16x16x32_bf16 v[136:139], v[128:131], v[164:167], v[136:139]
	v_mfma_f32_16x16x32_bf16 v[116:119], v[108:111], v[172:175], v[116:119]
	v_mfma_f32_16x16x32_bf16 v[112:115], v[128:131], v[172:175], v[112:115]
	v_mfma_f32_16x16x32_bf16 v[92:95], v[108:111], v[180:183], v[92:95]
	v_mfma_f32_16x16x32_bf16 v[88:91], v[128:131], v[180:183], v[88:91]
	v_mfma_f32_16x16x32_bf16 v[76:79], v[108:111], v[210:213], v[76:79]
	v_mfma_f32_16x16x32_bf16 v[72:75], v[128:131], v[210:213], v[72:75]
	s_setprio 0
	s_setprio 1
	v_mfma_f32_16x16x32_bf16 v[132:135], v[144:147], v[160:163], v[132:135]
	v_mfma_f32_16x16x32_bf16 v[120:123], v[152:155], v[160:163], v[120:123]
	v_mfma_f32_16x16x32_bf16 v[100:103], v[144:147], v[168:171], v[100:103]
	v_mfma_f32_16x16x32_bf16 v[96:99], v[152:155], v[168:171], v[96:99]
	v_mfma_f32_16x16x32_bf16 v[84:87], v[144:147], v[176:179], v[84:87]
	v_mfma_f32_16x16x32_bf16 v[80:83], v[152:155], v[176:179], v[80:83]
	v_mfma_f32_16x16x32_bf16 v[68:71], v[144:147], v[206:209], v[68:71]
	v_mfma_f32_16x16x32_bf16 v[64:67], v[152:155], v[206:209], v[64:67]
	v_mfma_f32_16x16x32_bf16 v[132:135], v[148:151], v[164:167], v[132:135]
	v_mfma_f32_16x16x32_bf16 v[120:123], v[156:159], v[164:167], v[120:123]
	v_mfma_f32_16x16x32_bf16 v[100:103], v[148:151], v[172:175], v[100:103]
	v_mfma_f32_16x16x32_bf16 v[96:99], v[156:159], v[172:175], v[96:99]
	v_mfma_f32_16x16x32_bf16 v[84:87], v[148:151], v[180:183], v[84:87]
	v_mfma_f32_16x16x32_bf16 v[80:83], v[156:159], v[180:183], v[80:83]
	v_mfma_f32_16x16x32_bf16 v[68:71], v[148:151], v[210:213], v[68:71]
	v_mfma_f32_16x16x32_bf16 v[64:67], v[156:159], v[210:213], v[64:67]
	s_setprio 0
	s_barrier
	s_add_i32 s88, s69, s13
	v_lshl_add_u64 v[196:197], s[48:49], 0, v[184:185]
	s_mov_b32 m0, s88
	ds_read_b128 v[160:163], v202 offset:16384
	ds_read_b128 v[164:167], v202 offset:17408
	ds_read_b128 v[168:171], v202 offset:18432
	ds_read_b128 v[172:175], v202 offset:19456
	ds_read_b128 v[176:179], v202 offset:20480
	ds_read_b128 v[180:183], v202 offset:21504
	ds_read_b128 v[206:209], v202 offset:22528
	ds_read_b128 v[210:213], v202 offset:23552
	global_load_lds_dwordx4 v[196:197], off
	s_add_i32 m0, s88, 0x2000
	s_add_u32 s88, s48, 0x40000
	v_lshl_add_u64 v[214:215], s[48:49], 0, v[186:187]
	s_addc_u32 s89, s49, 0
	s_add_i32 s90, s70, s13
	global_load_lds_dwordx4 v[214:215], off
	v_lshl_add_u64 v[216:217], s[88:89], 0, v[184:185]
	s_mov_b32 m0, s90
	v_lshl_add_u64 v[218:219], s[50:51], 0, v[186:187]
	global_load_lds_dwordx4 v[216:217], off
	v_lshl_add_u64 v[216:217], s[88:89], 0, v[186:187]
	s_add_i32 m0, s90, 0x2000
	s_nop 0
	global_load_lds_dwordx4 v[216:217], off
	v_lshl_add_u64 v[216:217], s[50:51], 0, v[184:185]
	s_mov_b32 m0, s52
	s_nop 0
	global_load_lds_dwordx4 v[216:217], off
	s_mov_b32 m0, s53
	s_nop 0
	global_load_lds_dwordx4 v[218:219], off
	s_waitcnt vmcnt(8)
	s_waitcnt lgkmcnt(0)
	s_setprio 1
	s_barrier
	v_mfma_f32_16x16x32_bf16 v[60:63], v[104:107], v[160:163], v[60:63]
	v_mfma_f32_16x16x32_bf16 v[56:59], v[124:127], v[160:163], v[56:59]
	v_mfma_f32_16x16x32_bf16 v[44:47], v[104:107], v[168:171], v[44:47]
	v_mfma_f32_16x16x32_bf16 v[40:43], v[124:127], v[168:171], v[40:43]
	v_mfma_f32_16x16x32_bf16 v[28:31], v[104:107], v[176:179], v[28:31]
	v_mfma_f32_16x16x32_bf16 v[24:27], v[124:127], v[176:179], v[24:27]
	v_mfma_f32_16x16x32_bf16 v[12:15], v[104:107], v[206:209], v[12:15]
	v_mfma_f32_16x16x32_bf16 v[8:11], v[124:127], v[206:209], v[8:11]
	v_mfma_f32_16x16x32_bf16 v[60:63], v[108:111], v[164:167], v[60:63]
	v_mfma_f32_16x16x32_bf16 v[56:59], v[128:131], v[164:167], v[56:59]
	v_mfma_f32_16x16x32_bf16 v[44:47], v[108:111], v[172:175], v[44:47]
	v_mfma_f32_16x16x32_bf16 v[40:43], v[128:131], v[172:175], v[40:43]
	v_mfma_f32_16x16x32_bf16 v[28:31], v[108:111], v[180:183], v[28:31]
	v_mfma_f32_16x16x32_bf16 v[24:27], v[128:131], v[180:183], v[24:27]
	v_mfma_f32_16x16x32_bf16 v[12:15], v[108:111], v[210:213], v[12:15]
	v_mfma_f32_16x16x32_bf16 v[8:11], v[128:131], v[210:213], v[8:11]
	s_setprio 0
	s_setprio 1
	v_mfma_f32_16x16x32_bf16 v[52:55], v[144:147], v[160:163], v[52:55]
	v_mfma_f32_16x16x32_bf16 v[48:51], v[152:155], v[160:163], v[48:51]
	v_mfma_f32_16x16x32_bf16 v[36:39], v[144:147], v[168:171], v[36:39]
	v_mfma_f32_16x16x32_bf16 v[32:35], v[152:155], v[168:171], v[32:35]
	v_mfma_f32_16x16x32_bf16 v[20:23], v[144:147], v[176:179], v[20:23]
	v_mfma_f32_16x16x32_bf16 v[16:19], v[152:155], v[176:179], v[16:19]
	v_mfma_f32_16x16x32_bf16 v[4:7], v[144:147], v[206:209], v[4:7]
	v_mfma_f32_16x16x32_bf16 v[0:3], v[152:155], v[206:209], v[0:3]
	v_mfma_f32_16x16x32_bf16 v[52:55], v[148:151], v[164:167], v[52:55]
	v_mfma_f32_16x16x32_bf16 v[48:51], v[156:159], v[164:167], v[48:51]
	v_mfma_f32_16x16x32_bf16 v[36:39], v[148:151], v[172:175], v[36:39]
	v_mfma_f32_16x16x32_bf16 v[32:35], v[156:159], v[172:175], v[32:35]
	v_mfma_f32_16x16x32_bf16 v[20:23], v[148:151], v[180:183], v[20:23]
	v_mfma_f32_16x16x32_bf16 v[16:19], v[156:159], v[180:183], v[16:19]
	v_mfma_f32_16x16x32_bf16 v[4:7], v[148:151], v[210:213], v[4:7]
	v_mfma_f32_16x16x32_bf16 v[0:3], v[156:159], v[210:213], v[0:3]
	s_setprio 0
	s_barrier
	s_add_i32 s88, 0, 0x18000
	s_add_i32 s89, 0, 0x1c000
	v_add_u32_e32 v128, s88, v199
	v_add_u32_e32 v156, s89, v199
	ds_read_b128 v[104:107], v128
	ds_read_b128 v[108:111], v128 offset:1024
	ds_read_b128 v[124:127], v128 offset:2048
	ds_read_b128 v[128:131], v128 offset:3072
	ds_read_b128 v[144:147], v156
	ds_read_b128 v[148:151], v156 offset:1024
	ds_read_b128 v[152:155], v156 offset:2048
	ds_read_b128 v[156:159], v156 offset:3072
	s_add_u32 s50, s50, 0x40000
	s_addc_u32 s51, s51, 0
	s_mov_b32 m0, s54
	v_lshl_add_u64 v[220:221], s[50:51], 0, v[184:185]
	ds_read_b128 v[160:163], v202 offset:32768
	ds_read_b128 v[164:167], v202 offset:33792
	ds_read_b128 v[168:171], v202 offset:34816
	ds_read_b128 v[172:175], v202 offset:35840
	ds_read_b128 v[176:179], v202 offset:36864
	ds_read_b128 v[180:183], v202 offset:37888
	ds_read_b128 v[206:209], v202 offset:38912
	ds_read_b128 v[210:213], v202 offset:39936
	global_load_lds_dwordx4 v[220:221], off
	v_lshl_add_u64 v[220:221], s[50:51], 0, v[186:187]
	s_mov_b32 m0, s55
	s_nop 0
	global_load_lds_dwordx4 v[220:221], off
	s_waitcnt vmcnt(8)
	s_waitcnt lgkmcnt(0)
	s_setprio 1
	s_barrier
	v_mfma_f32_16x16x32_bf16 v[140:143], v[104:107], v[160:163], v[140:143]
	v_mfma_f32_16x16x32_bf16 v[136:139], v[124:127], v[160:163], v[136:139]
	v_mfma_f32_16x16x32_bf16 v[116:119], v[104:107], v[168:171], v[116:119]
	v_mfma_f32_16x16x32_bf16 v[112:115], v[124:127], v[168:171], v[112:115]
	v_mfma_f32_16x16x32_bf16 v[92:95], v[104:107], v[176:179], v[92:95]
	v_mfma_f32_16x16x32_bf16 v[88:91], v[124:127], v[176:179], v[88:91]
	v_mfma_f32_16x16x32_bf16 v[76:79], v[104:107], v[206:209], v[76:79]
	v_mfma_f32_16x16x32_bf16 v[72:75], v[124:127], v[206:209], v[72:75]
	v_mfma_f32_16x16x32_bf16 v[140:143], v[108:111], v[164:167], v[140:143]
	v_mfma_f32_16x16x32_bf16 v[136:139], v[128:131], v[164:167], v[136:139]
	v_mfma_f32_16x16x32_bf16 v[116:119], v[108:111], v[172:175], v[116:119]
	v_mfma_f32_16x16x32_bf16 v[112:115], v[128:131], v[172:175], v[112:115]
	v_mfma_f32_16x16x32_bf16 v[92:95], v[108:111], v[180:183], v[92:95]
	v_mfma_f32_16x16x32_bf16 v[88:91], v[128:131], v[180:183], v[88:91]
	v_mfma_f32_16x16x32_bf16 v[76:79], v[108:111], v[210:213], v[76:79]
	v_mfma_f32_16x16x32_bf16 v[72:75], v[128:131], v[210:213], v[72:75]
	s_setprio 0
	s_setprio 1
	v_mfma_f32_16x16x32_bf16 v[132:135], v[144:147], v[160:163], v[132:135]
	v_mfma_f32_16x16x32_bf16 v[120:123], v[152:155], v[160:163], v[120:123]
	v_mfma_f32_16x16x32_bf16 v[100:103], v[144:147], v[168:171], v[100:103]
	v_mfma_f32_16x16x32_bf16 v[96:99], v[152:155], v[168:171], v[96:99]
	v_mfma_f32_16x16x32_bf16 v[84:87], v[144:147], v[176:179], v[84:87]
	v_mfma_f32_16x16x32_bf16 v[80:83], v[152:155], v[176:179], v[80:83]
	v_mfma_f32_16x16x32_bf16 v[68:71], v[144:147], v[206:209], v[68:71]
	v_mfma_f32_16x16x32_bf16 v[64:67], v[152:155], v[206:209], v[64:67]
	v_mfma_f32_16x16x32_bf16 v[132:135], v[148:151], v[164:167], v[132:135]
	v_mfma_f32_16x16x32_bf16 v[120:123], v[156:159], v[164:167], v[120:123]
	v_mfma_f32_16x16x32_bf16 v[100:103], v[148:151], v[172:175], v[100:103]
	v_mfma_f32_16x16x32_bf16 v[96:99], v[156:159], v[172:175], v[96:99]
	v_mfma_f32_16x16x32_bf16 v[84:87], v[148:151], v[180:183], v[84:87]
	v_mfma_f32_16x16x32_bf16 v[80:83], v[156:159], v[180:183], v[80:83]
	v_mfma_f32_16x16x32_bf16 v[68:71], v[148:151], v[210:213], v[68:71]
	v_mfma_f32_16x16x32_bf16 v[64:67], v[156:159], v[210:213], v[64:67]
	s_setprio 0
	s_barrier
	s_add_i32 s50, s88, s13
	v_lshl_add_u64 v[196:197], v[196:197], 0, s[30:31]
	s_mov_b32 m0, s50
	ds_read_b128 v[160:163], v202 offset:49152
	ds_read_b128 v[164:167], v202 offset:50176
	ds_read_b128 v[168:171], v202 offset:51200
	ds_read_b128 v[172:175], v202 offset:52224
	ds_read_b128 v[176:179], v202 offset:53248
	ds_read_b128 v[180:183], v202 offset:54272
	ds_read_b128 v[206:209], v202 offset:55296
	ds_read_b128 v[210:213], v202 offset:56320
	global_load_lds_dwordx4 v[196:197], off
	s_add_i32 m0, s50, 0x2000
	s_add_u32 s48, s48, 0x40080
	v_lshl_add_u64 v[196:197], v[214:215], 0, s[30:31]
	s_addc_u32 s49, s49, 0
	s_add_i32 s50, s89, s13
	global_load_lds_dwordx4 v[196:197], off
	v_lshl_add_u64 v[196:197], s[48:49], 0, v[184:185]
	s_mov_b32 m0, s50
	s_nop 0
	global_load_lds_dwordx4 v[196:197], off
	v_lshl_add_u64 v[196:197], s[48:49], 0, v[186:187]
	s_add_i32 m0, s50, 0x2000
	s_nop 0
	global_load_lds_dwordx4 v[196:197], off
	v_lshl_add_u64 v[196:197], v[216:217], 0, s[30:31]
	s_mov_b32 m0, s61
	s_nop 0
	global_load_lds_dwordx4 v[196:197], off
	v_lshl_add_u64 v[196:197], v[218:219], 0, s[30:31]
	s_mov_b32 m0, s62
	s_nop 0
	global_load_lds_dwordx4 v[196:197], off
	s_waitcnt vmcnt(8)
	s_waitcnt lgkmcnt(0)
	s_setprio 1
	s_barrier
	v_mfma_f32_16x16x32_bf16 v[60:63], v[104:107], v[160:163], v[60:63]
	v_mfma_f32_16x16x32_bf16 v[56:59], v[124:127], v[160:163], v[56:59]
	v_mfma_f32_16x16x32_bf16 v[44:47], v[104:107], v[168:171], v[44:47]
	v_mfma_f32_16x16x32_bf16 v[40:43], v[124:127], v[168:171], v[40:43]
	v_mfma_f32_16x16x32_bf16 v[28:31], v[104:107], v[176:179], v[28:31]
	v_mfma_f32_16x16x32_bf16 v[24:27], v[124:127], v[176:179], v[24:27]
	v_mfma_f32_16x16x32_bf16 v[12:15], v[104:107], v[206:209], v[12:15]
	v_mfma_f32_16x16x32_bf16 v[8:11], v[124:127], v[206:209], v[8:11]
	v_mfma_f32_16x16x32_bf16 v[60:63], v[108:111], v[164:167], v[60:63]
	v_mfma_f32_16x16x32_bf16 v[56:59], v[128:131], v[164:167], v[56:59]
	v_mfma_f32_16x16x32_bf16 v[44:47], v[108:111], v[172:175], v[44:47]
	v_mfma_f32_16x16x32_bf16 v[40:43], v[128:131], v[172:175], v[40:43]
	v_mfma_f32_16x16x32_bf16 v[28:31], v[108:111], v[180:183], v[28:31]
	v_mfma_f32_16x16x32_bf16 v[24:27], v[128:131], v[180:183], v[24:27]
	v_mfma_f32_16x16x32_bf16 v[12:15], v[108:111], v[210:213], v[12:15]
	v_mfma_f32_16x16x32_bf16 v[8:11], v[128:131], v[210:213], v[8:11]
	s_setprio 0
	s_setprio 1
	v_mfma_f32_16x16x32_bf16 v[52:55], v[144:147], v[160:163], v[52:55]
	v_mfma_f32_16x16x32_bf16 v[48:51], v[152:155], v[160:163], v[48:51]
	v_mfma_f32_16x16x32_bf16 v[36:39], v[144:147], v[168:171], v[36:39]
	v_mfma_f32_16x16x32_bf16 v[32:35], v[152:155], v[168:171], v[32:35]
	v_mfma_f32_16x16x32_bf16 v[20:23], v[144:147], v[176:179], v[20:23]
	v_mfma_f32_16x16x32_bf16 v[16:19], v[152:155], v[176:179], v[16:19]
	v_mfma_f32_16x16x32_bf16 v[4:7], v[144:147], v[206:209], v[4:7]
	v_mfma_f32_16x16x32_bf16 v[0:3], v[152:155], v[206:209], v[0:3]
	v_mfma_f32_16x16x32_bf16 v[52:55], v[148:151], v[164:167], v[52:55]
	v_mfma_f32_16x16x32_bf16 v[48:51], v[156:159], v[164:167], v[48:51]
	v_mfma_f32_16x16x32_bf16 v[36:39], v[148:151], v[172:175], v[36:39]
	v_mfma_f32_16x16x32_bf16 v[32:35], v[156:159], v[172:175], v[32:35]
	v_mfma_f32_16x16x32_bf16 v[20:23], v[148:151], v[180:183], v[20:23]
	v_mfma_f32_16x16x32_bf16 v[16:19], v[156:159], v[180:183], v[16:19]
	v_mfma_f32_16x16x32_bf16 v[4:7], v[148:151], v[210:213], v[4:7]
	v_mfma_f32_16x16x32_bf16 v[0:3], v[156:159], v[210:213], v[0:3]
	s_setprio 0
	s_barrier
	s_add_i32 s87, s87, 2
	s_add_u32 s46, s46, 0x100
	s_addc_u32 s47, s47, 0
	s_add_u32 s85, s85, 0x100
	s_addc_u32 s86, s86, 0
	s_cmp_gt_u32 s87, 13
	s_cbranch_scc0 .LBB0_504
	s_and_b64 vcc, exec, s[34:35]
	s_cbranch_vccz .LBB0_507
	s_barrier

.LBB0_552:
	ds_read_b128 v[128:131], v173
	ds_read_b128 v[132:135], v173 offset:1024
	ds_read_b128 v[136:139], v173 offset:2048
	ds_read_b128 v[140:143], v173 offset:3072
	ds_read_b128 v[160:163], v179
	ds_read_b128 v[174:177], v179 offset:1024
	ds_read_b128 v[194:197], v179 offset:2048
	ds_read_b128 v[198:201], v179 offset:3072
	s_add_u32 s57, s62, 0xfffc0080
	s_addc_u32 s64, s63, -1
	s_cmp_eq_u32 s55, 12
	s_cselect_b32 s67, s9, s64
	s_cselect_b32 s66, s11, s57
	s_cselect_b32 s65, s13, s23
	s_cselect_b32 s64, s16, s22
	v_lshl_add_u64 v[166:167], s[62:63], 0, v[152:153]
	s_add_i32 m0, s86, 0xc000
	ds_read_b128 v[202:205], v183
	ds_read_b128 v[206:209], v183 offset:1024
	ds_read_b128 v[210:213], v183 offset:2048
	ds_read_b128 v[214:217], v183 offset:3072
	ds_read_b128 v[218:221], v183 offset:4096
	ds_read_b128 v[222:225], v183 offset:5120
	ds_read_b128 v[226:229], v183 offset:6144
	ds_read_b128 v[230:233], v183 offset:7168
	global_load_lds_dwordx4 v[166:167], off
	v_lshl_add_u64 v[166:167], s[62:63], 0, v[154:155]
	s_add_i32 m0, s86, 0xe000
	s_nop 0
	global_load_lds_dwordx4 v[166:167], off
	s_waitcnt vmcnt(8)
	s_waitcnt lgkmcnt(0)
	s_setprio 1
	s_barrier
	v_mfma_f32_16x16x32_bf16 v[124:127], v[128:131], v[202:205], v[124:127]
	v_mfma_f32_16x16x32_bf16 v[120:123], v[136:139], v[202:205], v[120:123]
	v_mfma_f32_16x16x32_bf16 v[108:111], v[128:131], v[210:213], v[108:111]
	v_mfma_f32_16x16x32_bf16 v[104:107], v[136:139], v[210:213], v[104:107]
	v_mfma_f32_16x16x32_bf16 v[92:95], v[128:131], v[218:221], v[92:95]
	v_mfma_f32_16x16x32_bf16 v[88:91], v[136:139], v[218:221], v[88:91]
	v_mfma_f32_16x16x32_bf16 v[76:79], v[128:131], v[226:229], v[76:79]
	v_mfma_f32_16x16x32_bf16 v[72:75], v[136:139], v[226:229], v[72:75]
	v_mfma_f32_16x16x32_bf16 v[124:127], v[132:135], v[206:209], v[124:127]
	v_mfma_f32_16x16x32_bf16 v[120:123], v[140:143], v[206:209], v[120:123]
	v_mfma_f32_16x16x32_bf16 v[108:111], v[132:135], v[214:217], v[108:111]
	v_mfma_f32_16x16x32_bf16 v[104:107], v[140:143], v[214:217], v[104:107]
	v_mfma_f32_16x16x32_bf16 v[92:95], v[132:135], v[222:225], v[92:95]
	v_mfma_f32_16x16x32_bf16 v[88:91], v[140:143], v[222:225], v[88:91]
	v_mfma_f32_16x16x32_bf16 v[76:79], v[132:135], v[230:233], v[76:79]
	v_mfma_f32_16x16x32_bf16 v[72:75], v[140:143], v[230:233], v[72:75]
	s_setprio 0
	s_setprio 1
	v_mfma_f32_16x16x32_bf16 v[116:119], v[160:163], v[202:205], v[116:119]
	v_mfma_f32_16x16x32_bf16 v[112:115], v[194:197], v[202:205], v[112:115]
	v_mfma_f32_16x16x32_bf16 v[100:103], v[160:163], v[210:213], v[100:103]
	v_mfma_f32_16x16x32_bf16 v[96:99], v[194:197], v[210:213], v[96:99]
	v_mfma_f32_16x16x32_bf16 v[84:87], v[160:163], v[218:221], v[84:87]
	v_mfma_f32_16x16x32_bf16 v[80:83], v[194:197], v[218:221], v[80:83]
	v_mfma_f32_16x16x32_bf16 v[68:71], v[160:163], v[226:229], v[68:71]
	v_mfma_f32_16x16x32_bf16 v[64:67], v[194:197], v[226:229], v[64:67]
	v_mfma_f32_16x16x32_bf16 v[116:119], v[174:177], v[206:209], v[116:119]
	v_mfma_f32_16x16x32_bf16 v[112:115], v[198:201], v[206:209], v[112:115]
	v_mfma_f32_16x16x32_bf16 v[100:103], v[174:177], v[214:217], v[100:103]
	v_mfma_f32_16x16x32_bf16 v[96:99], v[198:201], v[214:217], v[96:99]
	v_mfma_f32_16x16x32_bf16 v[84:87], v[174:177], v[222:225], v[84:87]
	v_mfma_f32_16x16x32_bf16 v[80:83], v[198:201], v[222:225], v[80:83]
	v_mfma_f32_16x16x32_bf16 v[68:71], v[174:177], v[230:233], v[68:71]
	v_mfma_f32_16x16x32_bf16 v[64:67], v[198:201], v[230:233], v[64:67]
	s_setprio 0
	s_barrier
	s_add_i32 s57, s0, s85
	v_lshl_add_u64 v[166:167], s[64:65], 0, v[144:145]
	s_mov_b32 m0, s57
	ds_read_b128 v[202:205], v183 offset:16384
	ds_read_b128 v[206:209], v183 offset:17408
	ds_read_b128 v[210:213], v183 offset:18432
	ds_read_b128 v[214:217], v183 offset:19456
	ds_read_b128 v[218:221], v183 offset:20480
	ds_read_b128 v[222:225], v183 offset:21504
	ds_read_b128 v[226:229], v183 offset:22528
	ds_read_b128 v[230:233], v183 offset:23552
	global_load_lds_dwordx4 v[166:167], off
	s_add_i32 m0, s57, 0x2000
	s_add_u32 s68, s64, 0x40000
	v_lshl_add_u64 v[170:171], s[64:65], 0, v[146:147]
	s_addc_u32 s69, s65, 0
	s_add_i32 s57, s1, s85
	global_load_lds_dwordx4 v[170:171], off
	v_lshl_add_u64 v[180:181], s[68:69], 0, v[144:145]
	s_mov_b32 m0, s57
	v_lshl_add_u64 v[184:185], s[66:67], 0, v[146:147]
	global_load_lds_dwordx4 v[180:181], off
	v_lshl_add_u64 v[180:181], s[68:69], 0, v[146:147]
	s_add_i32 m0, s57, 0x2000
	s_nop 0
	global_load_lds_dwordx4 v[180:181], off
	v_lshl_add_u64 v[180:181], s[66:67], 0, v[144:145]
	s_mov_b32 m0, s86
	s_nop 0
	global_load_lds_dwordx4 v[180:181], off
	s_mov_b32 m0, s87
	s_nop 0
	global_load_lds_dwordx4 v[184:185], off
	s_waitcnt vmcnt(8)
	s_waitcnt lgkmcnt(0)
	s_setprio 1
	s_barrier
	v_mfma_f32_16x16x32_bf16 v[60:63], v[128:131], v[202:205], v[60:63]
	v_mfma_f32_16x16x32_bf16 v[56:59], v[136:139], v[202:205], v[56:59]
	v_mfma_f32_16x16x32_bf16 v[44:47], v[128:131], v[210:213], v[44:47]
	v_mfma_f32_16x16x32_bf16 v[40:43], v[136:139], v[210:213], v[40:43]
	v_mfma_f32_16x16x32_bf16 v[28:31], v[128:131], v[218:221], v[28:31]
	v_mfma_f32_16x16x32_bf16 v[24:27], v[136:139], v[218:221], v[24:27]
	v_mfma_f32_16x16x32_bf16 v[12:15], v[128:131], v[226:229], v[12:15]
	v_mfma_f32_16x16x32_bf16 v[8:11], v[136:139], v[226:229], v[8:11]
	v_mfma_f32_16x16x32_bf16 v[60:63], v[132:135], v[206:209], v[60:63]
	v_mfma_f32_16x16x32_bf16 v[56:59], v[140:143], v[206:209], v[56:59]
	v_mfma_f32_16x16x32_bf16 v[44:47], v[132:135], v[214:217], v[44:47]
	v_mfma_f32_16x16x32_bf16 v[40:43], v[140:143], v[214:217], v[40:43]
	v_mfma_f32_16x16x32_bf16 v[28:31], v[132:135], v[222:225], v[28:31]
	v_mfma_f32_16x16x32_bf16 v[24:27], v[140:143], v[222:225], v[24:27]
	v_mfma_f32_16x16x32_bf16 v[12:15], v[132:135], v[230:233], v[12:15]
	v_mfma_f32_16x16x32_bf16 v[8:11], v[140:143], v[230:233], v[8:11]
	s_setprio 0
	s_setprio 1
	v_mfma_f32_16x16x32_bf16 v[52:55], v[160:163], v[202:205], v[52:55]
	v_mfma_f32_16x16x32_bf16 v[48:51], v[194:197], v[202:205], v[48:51]
	v_mfma_f32_16x16x32_bf16 v[36:39], v[160:163], v[210:213], v[36:39]
	v_mfma_f32_16x16x32_bf16 v[32:35], v[194:197], v[210:213], v[32:35]
	v_mfma_f32_16x16x32_bf16 v[20:23], v[160:163], v[218:221], v[20:23]
	v_mfma_f32_16x16x32_bf16 v[16:19], v[194:197], v[218:221], v[16:19]
	v_mfma_f32_16x16x32_bf16 v[4:7], v[160:163], v[226:229], v[4:7]
	v_mfma_f32_16x16x32_bf16 v[0:3], v[194:197], v[226:229], v[0:3]
	v_mfma_f32_16x16x32_bf16 v[52:55], v[174:177], v[206:209], v[52:55]
	v_mfma_f32_16x16x32_bf16 v[48:51], v[198:201], v[206:209], v[48:51]
	v_mfma_f32_16x16x32_bf16 v[36:39], v[174:177], v[214:217], v[36:39]
	v_mfma_f32_16x16x32_bf16 v[32:35], v[198:201], v[214:217], v[32:35]
	v_mfma_f32_16x16x32_bf16 v[20:23], v[174:177], v[222:225], v[20:23]
	v_mfma_f32_16x16x32_bf16 v[16:19], v[198:201], v[222:225], v[16:19]
	v_mfma_f32_16x16x32_bf16 v[4:7], v[174:177], v[230:233], v[4:7]
	v_mfma_f32_16x16x32_bf16 v[0:3], v[198:201], v[230:233], v[0:3]
	s_setprio 0
	s_barrier
	s_add_i32 s57, 0, 0x18000
	s_add_i32 s68, 0, 0x1c000
	v_add_u32_e32 v140, s57, v169
	v_add_u32_e32 v148, s68, v169
	ds_read_b128 v[128:131], v140
	ds_read_b128 v[132:135], v140 offset:1024
	ds_read_b128 v[136:139], v140 offset:2048
	ds_read_b128 v[140:143], v140 offset:3072
	ds_read_b128 v[160:163], v148
	ds_read_b128 v[174:177], v148 offset:1024
	ds_read_b128 v[194:197], v148 offset:2048
	ds_read_b128 v[198:201], v148 offset:3072
	s_add_u32 s66, s66, 0x40000
	s_addc_u32 s67, s67, 0
	s_mov_b32 m0, s88
	v_lshl_add_u64 v[188:189], s[66:67], 0, v[144:145]
	ds_read_b128 v[202:205], v183 offset:32768
	ds_read_b128 v[206:209], v183 offset:33792
	ds_read_b128 v[210:213], v183 offset:34816
	ds_read_b128 v[214:217], v183 offset:35840
	ds_read_b128 v[218:221], v183 offset:36864
	ds_read_b128 v[222:225], v183 offset:37888
	ds_read_b128 v[226:229], v183 offset:38912
	ds_read_b128 v[230:233], v183 offset:39936
	global_load_lds_dwordx4 v[188:189], off
	v_lshl_add_u64 v[188:189], s[66:67], 0, v[146:147]
	s_mov_b32 m0, s89
	s_nop 0
	global_load_lds_dwordx4 v[188:189], off
	s_waitcnt vmcnt(8)
	s_waitcnt lgkmcnt(0)
	s_setprio 1
	s_barrier
	v_mfma_f32_16x16x32_bf16 v[124:127], v[128:131], v[202:205], v[124:127]
	v_mfma_f32_16x16x32_bf16 v[120:123], v[136:139], v[202:205], v[120:123]
	v_mfma_f32_16x16x32_bf16 v[108:111], v[128:131], v[210:213], v[108:111]
	v_mfma_f32_16x16x32_bf16 v[104:107], v[136:139], v[210:213], v[104:107]
	v_mfma_f32_16x16x32_bf16 v[92:95], v[128:131], v[218:221], v[92:95]
	v_mfma_f32_16x16x32_bf16 v[88:91], v[136:139], v[218:221], v[88:91]
	v_mfma_f32_16x16x32_bf16 v[76:79], v[128:131], v[226:229], v[76:79]
	v_mfma_f32_16x16x32_bf16 v[72:75], v[136:139], v[226:229], v[72:75]
	v_mfma_f32_16x16x32_bf16 v[124:127], v[132:135], v[206:209], v[124:127]
	v_mfma_f32_16x16x32_bf16 v[120:123], v[140:143], v[206:209], v[120:123]
	v_mfma_f32_16x16x32_bf16 v[108:111], v[132:135], v[214:217], v[108:111]
	v_mfma_f32_16x16x32_bf16 v[104:107], v[140:143], v[214:217], v[104:107]
	v_mfma_f32_16x16x32_bf16 v[92:95], v[132:135], v[222:225], v[92:95]
	v_mfma_f32_16x16x32_bf16 v[88:91], v[140:143], v[222:225], v[88:91]
	v_mfma_f32_16x16x32_bf16 v[76:79], v[132:135], v[230:233], v[76:79]
	v_mfma_f32_16x16x32_bf16 v[72:75], v[140:143], v[230:233], v[72:75]
	s_setprio 0
	s_setprio 1
	v_mfma_f32_16x16x32_bf16 v[116:119], v[160:163], v[202:205], v[116:119]
	v_mfma_f32_16x16x32_bf16 v[112:115], v[194:197], v[202:205], v[112:115]
	v_mfma_f32_16x16x32_bf16 v[100:103], v[160:163], v[210:213], v[100:103]
	v_mfma_f32_16x16x32_bf16 v[96:99], v[194:197], v[210:213], v[96:99]
	v_mfma_f32_16x16x32_bf16 v[84:87], v[160:163], v[218:221], v[84:87]
	v_mfma_f32_16x16x32_bf16 v[80:83], v[194:197], v[218:221], v[80:83]
	v_mfma_f32_16x16x32_bf16 v[68:71], v[160:163], v[226:229], v[68:71]
	v_mfma_f32_16x16x32_bf16 v[64:67], v[194:197], v[226:229], v[64:67]
	v_mfma_f32_16x16x32_bf16 v[116:119], v[174:177], v[206:209], v[116:119]
	v_mfma_f32_16x16x32_bf16 v[112:115], v[198:201], v[206:209], v[112:115]
	v_mfma_f32_16x16x32_bf16 v[100:103], v[174:177], v[214:217], v[100:103]
	v_mfma_f32_16x16x32_bf16 v[96:99], v[198:201], v[214:217], v[96:99]
	v_mfma_f32_16x16x32_bf16 v[84:87], v[174:177], v[222:225], v[84:87]
	v_mfma_f32_16x16x32_bf16 v[80:83], v[198:201], v[222:225], v[80:83]
	v_mfma_f32_16x16x32_bf16 v[68:71], v[174:177], v[230:233], v[68:71]
	v_mfma_f32_16x16x32_bf16 v[64:67], v[198:201], v[230:233], v[64:67]
	s_setprio 0
	s_barrier
	s_add_i32 s57, s57, s85
	v_lshl_add_u64 v[166:167], v[166:167], 0, s[42:43]
	s_mov_b32 m0, s57
	ds_read_b128 v[202:205], v183 offset:49152
	ds_read_b128 v[206:209], v183 offset:50176
	ds_read_b128 v[210:213], v183 offset:51200
	ds_read_b128 v[214:217], v183 offset:52224
	ds_read_b128 v[218:221], v183 offset:53248
	ds_read_b128 v[222:225], v183 offset:54272
	ds_read_b128 v[226:229], v183 offset:55296
	ds_read_b128 v[230:233], v183 offset:56320
	global_load_lds_dwordx4 v[166:167], off
	s_add_i32 m0, s57, 0x2000
	s_add_u32 s64, s64, 0x40080
	v_lshl_add_u64 v[166:167], v[170:171], 0, s[42:43]
	s_addc_u32 s65, s65, 0
	s_add_i32 s57, s68, s85
	global_load_lds_dwordx4 v[166:167], off
	v_lshl_add_u64 v[166:167], s[64:65], 0, v[144:145]
	s_mov_b32 m0, s57
	s_nop 0
	global_load_lds_dwordx4 v[166:167], off
	v_lshl_add_u64 v[166:167], s[64:65], 0, v[146:147]
	s_add_i32 m0, s57, 0x2000
	s_nop 0
	global_load_lds_dwordx4 v[166:167], off
	v_lshl_add_u64 v[166:167], v[180:181], 0, s[42:43]
	s_mov_b32 m0, s94
	s_nop 0
	global_load_lds_dwordx4 v[166:167], off
	v_lshl_add_u64 v[166:167], v[184:185], 0, s[42:43]
	s_mov_b32 m0, s95
	s_nop 0
	global_load_lds_dwordx4 v[166:167], off
	s_waitcnt vmcnt(8)
	s_waitcnt lgkmcnt(0)
	s_setprio 1
	s_barrier
	v_mfma_f32_16x16x32_bf16 v[60:63], v[128:131], v[202:205], v[60:63]
	v_mfma_f32_16x16x32_bf16 v[56:59], v[136:139], v[202:205], v[56:59]
	v_mfma_f32_16x16x32_bf16 v[44:47], v[128:131], v[210:213], v[44:47]
	v_mfma_f32_16x16x32_bf16 v[40:43], v[136:139], v[210:213], v[40:43]
	v_mfma_f32_16x16x32_bf16 v[28:31], v[128:131], v[218:221], v[28:31]
	v_mfma_f32_16x16x32_bf16 v[24:27], v[136:139], v[218:221], v[24:27]
	v_mfma_f32_16x16x32_bf16 v[12:15], v[128:131], v[226:229], v[12:15]
	v_mfma_f32_16x16x32_bf16 v[8:11], v[136:139], v[226:229], v[8:11]
	v_mfma_f32_16x16x32_bf16 v[60:63], v[132:135], v[206:209], v[60:63]
	v_mfma_f32_16x16x32_bf16 v[56:59], v[140:143], v[206:209], v[56:59]
	v_mfma_f32_16x16x32_bf16 v[44:47], v[132:135], v[214:217], v[44:47]
	v_mfma_f32_16x16x32_bf16 v[40:43], v[140:143], v[214:217], v[40:43]
	v_mfma_f32_16x16x32_bf16 v[28:31], v[132:135], v[222:225], v[28:31]
	v_mfma_f32_16x16x32_bf16 v[24:27], v[140:143], v[222:225], v[24:27]
	v_mfma_f32_16x16x32_bf16 v[12:15], v[132:135], v[230:233], v[12:15]
	v_mfma_f32_16x16x32_bf16 v[8:11], v[140:143], v[230:233], v[8:11]
	s_setprio 0
	s_setprio 1
	v_mfma_f32_16x16x32_bf16 v[52:55], v[160:163], v[202:205], v[52:55]
	v_mfma_f32_16x16x32_bf16 v[48:51], v[194:197], v[202:205], v[48:51]
	v_mfma_f32_16x16x32_bf16 v[36:39], v[160:163], v[210:213], v[36:39]
	v_mfma_f32_16x16x32_bf16 v[32:35], v[194:197], v[210:213], v[32:35]
	v_mfma_f32_16x16x32_bf16 v[20:23], v[160:163], v[218:221], v[20:23]
	v_mfma_f32_16x16x32_bf16 v[16:19], v[194:197], v[218:221], v[16:19]
	v_mfma_f32_16x16x32_bf16 v[4:7], v[160:163], v[226:229], v[4:7]
	v_mfma_f32_16x16x32_bf16 v[0:3], v[194:197], v[226:229], v[0:3]
	v_mfma_f32_16x16x32_bf16 v[52:55], v[174:177], v[206:209], v[52:55]
	v_mfma_f32_16x16x32_bf16 v[48:51], v[198:201], v[206:209], v[48:51]
	v_mfma_f32_16x16x32_bf16 v[36:39], v[174:177], v[214:217], v[36:39]
	v_mfma_f32_16x16x32_bf16 v[32:35], v[198:201], v[214:217], v[32:35]
	v_mfma_f32_16x16x32_bf16 v[20:23], v[174:177], v[222:225], v[20:23]
	v_mfma_f32_16x16x32_bf16 v[16:19], v[198:201], v[222:225], v[16:19]
	v_mfma_f32_16x16x32_bf16 v[4:7], v[174:177], v[230:233], v[4:7]
	v_mfma_f32_16x16x32_bf16 v[0:3], v[198:201], v[230:233], v[0:3]
	s_setprio 0
	s_barrier
	s_add_i32 s55, s55, 2
	s_add_u32 s62, s62, 0x100
	s_addc_u32 s63, s63, 0
	s_add_u32 s22, s22, 0x100
	s_addc_u32 s23, s23, 0
	s_cmp_gt_u32 s55, 13
	s_cbranch_scc0 .LBB0_552
	s_and_b64 vcc, exec, s[44:45]
	s_cbranch_vccz .LBB0_555
	s_barrier

.LBB0_744:
	s_add_u32 s54, s42, s48
	s_addc_u32 s55, s43, s49
	s_add_u32 s52, s54, 0x100
	s_addc_u32 s53, s55, 0
	s_and_b64 s[50:51], s[46:47], exec
	s_cselect_b32 s51, s35, s53
	s_cselect_b32 s50, s82, s52
	s_add_u32 s48, s40, s48
	s_addc_u32 s49, s41, s49
	s_add_u32 s48, s48, 0x100
	s_addc_u32 s49, s49, 0
	s_and_b64 s[46:47], s[46:47], exec
	s_cselect_b32 s53, s31, s49
	s_cselect_b32 s52, s83, s48
	s_cselect_b32 s98, 1, 0
	s_add_u32 s56, s54, 0x10080
	ds_read_b128 v[150:153], v144
	ds_read_b128 v[154:157], v144 offset:1024
	ds_read_b128 v[158:161], v144 offset:2048
	ds_read_b128 v[162:165], v144 offset:3072
	ds_read_b128 v[166:169], v145
	ds_read_b128 v[170:173], v145 offset:1024
	ds_read_b128 v[174:177], v145 offset:2048
	ds_read_b128 v[178:181], v145 offset:3072
	s_addc_u32 s57, s55, 0
	s_add_i32 s93, s74, s60
	s_add_i32 m0, s61, 0xc000
	s_add_i32 s94, s61, 0xe000
	s_add_i32 s90, s93, 0x2000
	s_add_u32 s54, s52, 0x10000
	s_addc_u32 s55, s53, 0
	s_add_i32 s92, s75, s60
	s_add_i32 s91, s92, 0x2000
	s_add_i32 s89, 0, 0x18000
	s_add_i32 s88, 0, 0x1c000
	s_add_u32 s48, s50, 0x10000
	s_addc_u32 s49, s51, 0
	s_add_i32 s87, s89, s60
	s_add_i32 s85, s87, 0x2000
	s_add_u32 s46, s52, 0x10080
	s_addc_u32 s47, s53, 0
	s_add_i32 s86, s88, s60
	s_add_i32 s84, s86, 0x2000
	v_lshl_add_u64 v[138:139], s[56:57], 0, v[130:131]
	ds_read_b128 v[182:185], v146
	ds_read_b128 v[186:189], v146 offset:1024
	ds_read_b128 v[190:193], v146 offset:2048
	ds_read_b128 v[194:197], v146 offset:3072
	ds_read_b128 v[198:201], v146 offset:4096
	ds_read_b128 v[202:205], v146 offset:5120
	ds_read_b128 v[206:209], v146 offset:6144
	ds_read_b128 v[210:213], v146 offset:7168
	global_load_lds_dwordx4 v[138:139], off
	v_lshl_add_u64 v[138:139], s[56:57], 0, v[128:129]
	s_mov_b32 m0, s94
	s_nop 0
	global_load_lds_dwordx4 v[138:139], off
	s_waitcnt vmcnt(8)
	s_waitcnt lgkmcnt(0)
	s_setprio 1
	s_cmp_lg_u32 s98, 0
	s_cbranch_scc0 .Lkv_nopf
	v_lshl_add_u32 v138, s18, 8, v141
	v_ashrrev_i32_e32 v139, 31, v138
	v_lshl_add_u64 v[138:139], v[138:139], 4, s[14:15]
	global_load_dwordx4 v[222:225], v[138:139], off
	global_load_dwordx4 v[226:229], v[138:139], off offset:256
	global_load_dwordx4 v[230:233], v[138:139], off offset:512
	global_load_dwordx4 v[234:237], v[138:139], off offset:768
	global_load_dwordx4 v[238:241], v[138:139], off offset:2048
	global_load_dwordx4 v[242:245], v[138:139], off offset:2304
	global_load_dwordx4 v[248:251], v[138:139], off offset:2560
	global_load_dwordx4 v[252:255], v[138:139], off offset:2816
.Lkv_nopf:
	s_barrier
	v_mfma_f32_16x16x32_bf16 v[124:127], v[150:153], v[182:185], v[124:127]
	v_mfma_f32_16x16x32_bf16 v[120:123], v[158:161], v[182:185], v[120:123]
	v_mfma_f32_16x16x32_bf16 v[108:111], v[150:153], v[190:193], v[108:111]
	v_mfma_f32_16x16x32_bf16 v[104:107], v[158:161], v[190:193], v[104:107]
	v_mfma_f32_16x16x32_bf16 v[92:95], v[150:153], v[198:201], v[92:95]
	v_mfma_f32_16x16x32_bf16 v[88:91], v[158:161], v[198:201], v[88:91]
	v_mfma_f32_16x16x32_bf16 v[76:79], v[150:153], v[206:209], v[76:79]
	v_mfma_f32_16x16x32_bf16 v[72:75], v[158:161], v[206:209], v[72:75]
	v_mfma_f32_16x16x32_bf16 v[124:127], v[154:157], v[186:189], v[124:127]
	v_mfma_f32_16x16x32_bf16 v[120:123], v[162:165], v[186:189], v[120:123]
	v_mfma_f32_16x16x32_bf16 v[108:111], v[154:157], v[194:197], v[108:111]
	v_mfma_f32_16x16x32_bf16 v[104:107], v[162:165], v[194:197], v[104:107]
	v_mfma_f32_16x16x32_bf16 v[92:95], v[154:157], v[202:205], v[92:95]
	v_mfma_f32_16x16x32_bf16 v[88:91], v[162:165], v[202:205], v[88:91]
	v_mfma_f32_16x16x32_bf16 v[76:79], v[154:157], v[210:213], v[76:79]
	v_mfma_f32_16x16x32_bf16 v[72:75], v[162:165], v[210:213], v[72:75]
	s_setprio 0
	s_setprio 1
	v_mfma_f32_16x16x32_bf16 v[116:119], v[166:169], v[182:185], v[116:119]
	v_mfma_f32_16x16x32_bf16 v[112:115], v[174:177], v[182:185], v[112:115]
	v_mfma_f32_16x16x32_bf16 v[100:103], v[166:169], v[190:193], v[100:103]
	v_mfma_f32_16x16x32_bf16 v[96:99], v[174:177], v[190:193], v[96:99]
	v_mfma_f32_16x16x32_bf16 v[84:87], v[166:169], v[198:201], v[84:87]
	v_mfma_f32_16x16x32_bf16 v[80:83], v[174:177], v[198:201], v[80:83]
	v_mfma_f32_16x16x32_bf16 v[68:71], v[166:169], v[206:209], v[68:71]
	v_mfma_f32_16x16x32_bf16 v[64:67], v[174:177], v[206:209], v[64:67]
	v_mfma_f32_16x16x32_bf16 v[116:119], v[170:173], v[186:189], v[116:119]
	v_mfma_f32_16x16x32_bf16 v[112:115], v[178:181], v[186:189], v[112:115]
	v_mfma_f32_16x16x32_bf16 v[100:103], v[170:173], v[194:197], v[100:103]
	v_mfma_f32_16x16x32_bf16 v[96:99], v[178:181], v[194:197], v[96:99]
	v_mfma_f32_16x16x32_bf16 v[84:87], v[170:173], v[202:205], v[84:87]
	v_mfma_f32_16x16x32_bf16 v[80:83], v[178:181], v[202:205], v[80:83]
	v_mfma_f32_16x16x32_bf16 v[68:71], v[170:173], v[210:213], v[68:71]
	v_mfma_f32_16x16x32_bf16 v[64:67], v[178:181], v[210:213], v[64:67]
	s_setprio 0
	s_barrier
	s_mov_b32 m0, s93
	v_lshl_add_u64 v[138:139], s[52:53], 0, v[130:131]
	ds_read_b128 v[182:185], v146 offset:16384
	ds_read_b128 v[186:189], v146 offset:17408
	ds_read_b128 v[190:193], v146 offset:18432
	ds_read_b128 v[194:197], v146 offset:19456
	ds_read_b128 v[198:201], v146 offset:20480
	ds_read_b128 v[202:205], v146 offset:21504
	ds_read_b128 v[206:209], v146 offset:22528
	ds_read_b128 v[210:213], v146 offset:23552
	global_load_lds_dwordx4 v[138:139], off
	v_lshl_add_u64 v[214:215], s[52:53], 0, v[128:129]
	s_mov_b32 m0, s90
	v_lshl_add_u64 v[216:217], s[54:55], 0, v[130:131]
	global_load_lds_dwordx4 v[214:215], off
	s_mov_b32 m0, s92
	v_lshl_add_u64 v[218:219], s[50:51], 0, v[128:129]
	global_load_lds_dwordx4 v[216:217], off
	v_lshl_add_u64 v[216:217], s[54:55], 0, v[128:129]
	s_mov_b32 m0, s91
	s_nop 0
	global_load_lds_dwordx4 v[216:217], off
	v_lshl_add_u64 v[216:217], s[50:51], 0, v[130:131]
	s_mov_b32 m0, s61
	s_nop 0
	global_load_lds_dwordx4 v[216:217], off
	s_mov_b32 m0, s62
	s_nop 0
	global_load_lds_dwordx4 v[218:219], off
	s_waitcnt vmcnt(8)
	s_waitcnt lgkmcnt(0)
	s_setprio 1
	s_barrier
	v_mfma_f32_16x16x32_bf16 v[60:63], v[150:153], v[182:185], v[60:63]
	v_mfma_f32_16x16x32_bf16 v[56:59], v[158:161], v[182:185], v[56:59]
	v_mfma_f32_16x16x32_bf16 v[44:47], v[150:153], v[190:193], v[44:47]
	v_mfma_f32_16x16x32_bf16 v[40:43], v[158:161], v[190:193], v[40:43]
	v_mfma_f32_16x16x32_bf16 v[28:31], v[150:153], v[198:201], v[28:31]
	v_mfma_f32_16x16x32_bf16 v[24:27], v[158:161], v[198:201], v[24:27]
	v_mfma_f32_16x16x32_bf16 v[12:15], v[150:153], v[206:209], v[12:15]
	v_mfma_f32_16x16x32_bf16 v[8:11], v[158:161], v[206:209], v[8:11]
	v_mfma_f32_16x16x32_bf16 v[60:63], v[154:157], v[186:189], v[60:63]
	v_mfma_f32_16x16x32_bf16 v[56:59], v[162:165], v[186:189], v[56:59]
	v_mfma_f32_16x16x32_bf16 v[44:47], v[154:157], v[194:197], v[44:47]
	v_mfma_f32_16x16x32_bf16 v[40:43], v[162:165], v[194:197], v[40:43]
	v_mfma_f32_16x16x32_bf16 v[28:31], v[154:157], v[202:205], v[28:31]
	v_mfma_f32_16x16x32_bf16 v[24:27], v[162:165], v[202:205], v[24:27]
	v_mfma_f32_16x16x32_bf16 v[12:15], v[154:157], v[210:213], v[12:15]
	v_mfma_f32_16x16x32_bf16 v[8:11], v[162:165], v[210:213], v[8:11]
	s_setprio 0
	s_setprio 1
	v_mfma_f32_16x16x32_bf16 v[52:55], v[166:169], v[182:185], v[52:55]
	v_mfma_f32_16x16x32_bf16 v[48:51], v[174:177], v[182:185], v[48:51]
	v_mfma_f32_16x16x32_bf16 v[36:39], v[166:169], v[190:193], v[36:39]
	v_mfma_f32_16x16x32_bf16 v[32:35], v[174:177], v[190:193], v[32:35]
	v_mfma_f32_16x16x32_bf16 v[20:23], v[166:169], v[198:201], v[20:23]
	v_mfma_f32_16x16x32_bf16 v[16:19], v[174:177], v[198:201], v[16:19]
	v_mfma_f32_16x16x32_bf16 v[4:7], v[166:169], v[206:209], v[4:7]
	v_mfma_f32_16x16x32_bf16 v[0:3], v[174:177], v[206:209], v[0:3]
	v_mfma_f32_16x16x32_bf16 v[52:55], v[170:173], v[186:189], v[52:55]
	v_mfma_f32_16x16x32_bf16 v[48:51], v[178:181], v[186:189], v[48:51]
	v_mfma_f32_16x16x32_bf16 v[36:39], v[170:173], v[194:197], v[36:39]
	v_mfma_f32_16x16x32_bf16 v[32:35], v[178:181], v[194:197], v[32:35]
	v_mfma_f32_16x16x32_bf16 v[20:23], v[170:173], v[202:205], v[20:23]
	v_mfma_f32_16x16x32_bf16 v[16:19], v[178:181], v[202:205], v[16:19]
	v_mfma_f32_16x16x32_bf16 v[4:7], v[170:173], v[210:213], v[4:7]
	v_mfma_f32_16x16x32_bf16 v[0:3], v[178:181], v[210:213], v[0:3]
	s_setprio 0
	s_barrier
	v_add_u32_e32 v132, s89, v143
	ds_read_b128 v[150:153], v132
	ds_read_b128 v[154:157], v132 offset:1024
	ds_read_b128 v[158:161], v132 offset:2048
	ds_read_b128 v[162:165], v132 offset:3072
	v_add_u32_e32 v132, s88, v143
	ds_read_b128 v[166:169], v132
	ds_read_b128 v[170:173], v132 offset:1024
	ds_read_b128 v[174:177], v132 offset:2048
	ds_read_b128 v[178:181], v132 offset:3072
	s_mov_b32 m0, s63
	v_lshl_add_u64 v[220:221], s[48:49], 0, v[130:131]
	ds_read_b128 v[182:185], v146 offset:32768
	ds_read_b128 v[186:189], v146 offset:33792
	ds_read_b128 v[190:193], v146 offset:34816
	ds_read_b128 v[194:197], v146 offset:35840
	ds_read_b128 v[198:201], v146 offset:36864
	ds_read_b128 v[202:205], v146 offset:37888
	ds_read_b128 v[206:209], v146 offset:38912
	ds_read_b128 v[210:213], v146 offset:39936
	global_load_lds_dwordx4 v[220:221], off
	v_lshl_add_u64 v[220:221], s[48:49], 0, v[128:129]
	s_mov_b32 m0, s64
	s_nop 0
	global_load_lds_dwordx4 v[220:221], off
	s_waitcnt vmcnt(8)
	s_waitcnt lgkmcnt(0)
	s_setprio 1
	s_barrier
	v_mfma_f32_16x16x32_bf16 v[124:127], v[150:153], v[182:185], v[124:127]
	v_mfma_f32_16x16x32_bf16 v[120:123], v[158:161], v[182:185], v[120:123]
	v_mfma_f32_16x16x32_bf16 v[108:111], v[150:153], v[190:193], v[108:111]
	v_mfma_f32_16x16x32_bf16 v[104:107], v[158:161], v[190:193], v[104:107]
	v_mfma_f32_16x16x32_bf16 v[92:95], v[150:153], v[198:201], v[92:95]
	v_mfma_f32_16x16x32_bf16 v[88:91], v[158:161], v[198:201], v[88:91]
	v_mfma_f32_16x16x32_bf16 v[76:79], v[150:153], v[206:209], v[76:79]
	v_mfma_f32_16x16x32_bf16 v[72:75], v[158:161], v[206:209], v[72:75]
	v_mfma_f32_16x16x32_bf16 v[124:127], v[154:157], v[186:189], v[124:127]
	v_mfma_f32_16x16x32_bf16 v[120:123], v[162:165], v[186:189], v[120:123]
	v_mfma_f32_16x16x32_bf16 v[108:111], v[154:157], v[194:197], v[108:111]
	v_mfma_f32_16x16x32_bf16 v[104:107], v[162:165], v[194:197], v[104:107]
	v_mfma_f32_16x16x32_bf16 v[92:95], v[154:157], v[202:205], v[92:95]
	v_mfma_f32_16x16x32_bf16 v[88:91], v[162:165], v[202:205], v[88:91]
	v_mfma_f32_16x16x32_bf16 v[76:79], v[154:157], v[210:213], v[76:79]
	v_mfma_f32_16x16x32_bf16 v[72:75], v[162:165], v[210:213], v[72:75]
	s_setprio 0
	s_setprio 1
	v_mfma_f32_16x16x32_bf16 v[116:119], v[166:169], v[182:185], v[116:119]
	v_mfma_f32_16x16x32_bf16 v[112:115], v[174:177], v[182:185], v[112:115]
	v_mfma_f32_16x16x32_bf16 v[100:103], v[166:169], v[190:193], v[100:103]
	v_mfma_f32_16x16x32_bf16 v[96:99], v[174:177], v[190:193], v[96:99]
	v_mfma_f32_16x16x32_bf16 v[84:87], v[166:169], v[198:201], v[84:87]
	v_mfma_f32_16x16x32_bf16 v[80:83], v[174:177], v[198:201], v[80:83]
	v_mfma_f32_16x16x32_bf16 v[68:71], v[166:169], v[206:209], v[68:71]
	v_mfma_f32_16x16x32_bf16 v[64:67], v[174:177], v[206:209], v[64:67]
	v_mfma_f32_16x16x32_bf16 v[116:119], v[170:173], v[186:189], v[116:119]
	v_mfma_f32_16x16x32_bf16 v[112:115], v[178:181], v[186:189], v[112:115]
	v_mfma_f32_16x16x32_bf16 v[100:103], v[170:173], v[194:197], v[100:103]
	v_mfma_f32_16x16x32_bf16 v[96:99], v[178:181], v[194:197], v[96:99]
	v_mfma_f32_16x16x32_bf16 v[84:87], v[170:173], v[202:205], v[84:87]
	v_mfma_f32_16x16x32_bf16 v[80:83], v[178:181], v[202:205], v[80:83]
	v_mfma_f32_16x16x32_bf16 v[68:71], v[170:173], v[210:213], v[68:71]
	v_mfma_f32_16x16x32_bf16 v[64:67], v[178:181], v[210:213], v[64:67]
	s_setprio 0
	s_barrier
	s_mov_b32 m0, s87
	v_lshl_add_u64 v[138:139], v[138:139], 0, s[16:17]
	ds_read_b128 v[182:185], v146 offset:49152
	ds_read_b128 v[186:189], v146 offset:50176
	ds_read_b128 v[190:193], v146 offset:51200
	ds_read_b128 v[194:197], v146 offset:52224
	ds_read_b128 v[198:201], v146 offset:53248
	ds_read_b128 v[202:205], v146 offset:54272
	ds_read_b128 v[206:209], v146 offset:55296
	ds_read_b128 v[210:213], v146 offset:56320
	global_load_lds_dwordx4 v[138:139], off
	v_lshl_add_u64 v[138:139], v[214:215], 0, s[16:17]
	s_mov_b32 m0, s85
	s_nop 0
	global_load_lds_dwordx4 v[138:139], off
	v_lshl_add_u64 v[138:139], s[46:47], 0, v[130:131]
	s_mov_b32 m0, s86
	s_nop 0
	global_load_lds_dwordx4 v[138:139], off
	v_lshl_add_u64 v[138:139], s[46:47], 0, v[128:129]
	s_mov_b32 m0, s84
	s_nop 0
	global_load_lds_dwordx4 v[138:139], off
	v_lshl_add_u64 v[138:139], v[216:217], 0, s[16:17]
	s_mov_b32 m0, s70
	s_nop 0
	global_load_lds_dwordx4 v[138:139], off
	v_lshl_add_u64 v[138:139], v[218:219], 0, s[16:17]
	s_mov_b32 m0, s71
	s_nop 0
	global_load_lds_dwordx4 v[138:139], off
	s_waitcnt vmcnt(8)
	s_waitcnt lgkmcnt(0)
	s_setprio 1
	s_barrier
	v_mfma_f32_16x16x32_bf16 v[60:63], v[150:153], v[182:185], v[60:63]
	v_mfma_f32_16x16x32_bf16 v[56:59], v[158:161], v[182:185], v[56:59]
	v_mfma_f32_16x16x32_bf16 v[44:47], v[150:153], v[190:193], v[44:47]
	v_mfma_f32_16x16x32_bf16 v[40:43], v[158:161], v[190:193], v[40:43]
	v_mfma_f32_16x16x32_bf16 v[28:31], v[150:153], v[198:201], v[28:31]
	v_mfma_f32_16x16x32_bf16 v[24:27], v[158:161], v[198:201], v[24:27]
	v_mfma_f32_16x16x32_bf16 v[12:15], v[150:153], v[206:209], v[12:15]
	v_mfma_f32_16x16x32_bf16 v[8:11], v[158:161], v[206:209], v[8:11]
	v_mfma_f32_16x16x32_bf16 v[60:63], v[154:157], v[186:189], v[60:63]
	v_mfma_f32_16x16x32_bf16 v[56:59], v[162:165], v[186:189], v[56:59]
	v_mfma_f32_16x16x32_bf16 v[44:47], v[154:157], v[194:197], v[44:47]
	v_mfma_f32_16x16x32_bf16 v[40:43], v[162:165], v[194:197], v[40:43]
	v_mfma_f32_16x16x32_bf16 v[28:31], v[154:157], v[202:205], v[28:31]
	v_mfma_f32_16x16x32_bf16 v[24:27], v[162:165], v[202:205], v[24:27]
	v_mfma_f32_16x16x32_bf16 v[12:15], v[154:157], v[210:213], v[12:15]
	v_mfma_f32_16x16x32_bf16 v[8:11], v[162:165], v[210:213], v[8:11]
	s_setprio 0
	s_setprio 1
	v_mfma_f32_16x16x32_bf16 v[52:55], v[166:169], v[182:185], v[52:55]
	v_mfma_f32_16x16x32_bf16 v[48:51], v[174:177], v[182:185], v[48:51]
	v_mfma_f32_16x16x32_bf16 v[36:39], v[166:169], v[190:193], v[36:39]
	v_mfma_f32_16x16x32_bf16 v[32:35], v[174:177], v[190:193], v[32:35]
	v_mfma_f32_16x16x32_bf16 v[20:23], v[166:169], v[198:201], v[20:23]
	v_mfma_f32_16x16x32_bf16 v[16:19], v[174:177], v[198:201], v[16:19]
	v_mfma_f32_16x16x32_bf16 v[4:7], v[166:169], v[206:209], v[4:7]
	v_mfma_f32_16x16x32_bf16 v[0:3], v[174:177], v[206:209], v[0:3]
	v_mfma_f32_16x16x32_bf16 v[52:55], v[170:173], v[186:189], v[52:55]
	v_mfma_f32_16x16x32_bf16 v[48:51], v[178:181], v[186:189], v[48:51]
	v_mfma_f32_16x16x32_bf16 v[36:39], v[170:173], v[194:197], v[36:39]
	v_mfma_f32_16x16x32_bf16 v[32:35], v[178:181], v[194:197], v[32:35]
	v_mfma_f32_16x16x32_bf16 v[20:23], v[170:173], v[202:205], v[20:23]
	v_mfma_f32_16x16x32_bf16 v[16:19], v[178:181], v[202:205], v[16:19]
	v_mfma_f32_16x16x32_bf16 v[4:7], v[170:173], v[210:213], v[4:7]
	v_mfma_f32_16x16x32_bf16 v[0:3], v[178:181], v[210:213], v[0:3]
	s_setprio 0
	s_barrier
	s_andn2_b64 vcc, exec, s[44:45]
	s_mov_b64 s[46:47], -1
	s_mov_b64 s[44:45], 0
	s_mov_b64 s[48:49], 0x100
	s_cbranch_vccz .LBB0_744
	s_and_b64 vcc, exec, s[20:21]
	s_cbranch_vccz .LBB0_747
	s_barrier

.LBB0_771:
	ds_read_b128 v[84:87], v208
	ds_read_b128 v[100:103], v208 offset:1024
	ds_read_b128 v[120:123], v208 offset:2048
	ds_read_b128 v[140:143], v208 offset:3072
	ds_read_b128 v[144:147], v209
	ds_read_b128 v[148:151], v209 offset:1024
	ds_read_b128 v[152:155], v209 offset:2048
	ds_read_b128 v[170:173], v209 offset:3072
	s_add_u32 s6, s8, 0x100
	s_addc_u32 s7, s9, 0
	s_cmp_eq_u32 s83, 2
	s_cselect_b32 s41, s35, s7
	s_cselect_b32 s40, s34, s6
	s_cselect_b32 s39, s37, s82
	s_cselect_b32 s38, s36, s81
	v_lshl_add_u64 v[214:215], s[8:9], 0, v[162:163]
	s_add_i32 m0, s42, 0xc000
	ds_read_b128 v[174:177], v210
	ds_read_b128 v[178:181], v210 offset:1024
	ds_read_b128 v[182:185], v210 offset:2048
	ds_read_b128 v[186:189], v210 offset:3072
	ds_read_b128 v[190:193], v210 offset:4096
	ds_read_b128 v[194:197], v210 offset:5120
	ds_read_b128 v[198:201], v210 offset:6144
	ds_read_b128 v[202:205], v210 offset:7168
	global_load_lds_dwordx4 v[214:215], off
	v_lshl_add_u64 v[214:215], s[8:9], 0, v[164:165]
	s_add_i32 m0, s42, 0xe000
	s_nop 0
	global_load_lds_dwordx4 v[214:215], off
	s_waitcnt vmcnt(8)
	s_waitcnt lgkmcnt(0)
	s_setprio 1
	s_barrier
	v_mfma_f32_16x16x32_bf16 v[136:139], v[84:87], v[174:177], v[136:139]
	v_mfma_f32_16x16x32_bf16 v[132:135], v[120:123], v[174:177], v[132:135]
	v_mfma_f32_16x16x32_bf16 v[116:119], v[84:87], v[182:185], v[116:119]
	v_mfma_f32_16x16x32_bf16 v[112:115], v[120:123], v[182:185], v[112:115]
	v_mfma_f32_16x16x32_bf16 v[96:99], v[84:87], v[190:193], v[96:99]
	v_mfma_f32_16x16x32_bf16 v[92:95], v[120:123], v[190:193], v[92:95]
	v_mfma_f32_16x16x32_bf16 v[76:79], v[84:87], v[198:201], v[76:79]
	v_mfma_f32_16x16x32_bf16 v[72:75], v[120:123], v[198:201], v[72:75]
	v_mfma_f32_16x16x32_bf16 v[136:139], v[100:103], v[178:181], v[136:139]
	v_mfma_f32_16x16x32_bf16 v[132:135], v[140:143], v[178:181], v[132:135]
	v_mfma_f32_16x16x32_bf16 v[116:119], v[100:103], v[186:189], v[116:119]
	v_mfma_f32_16x16x32_bf16 v[112:115], v[140:143], v[186:189], v[112:115]
	v_mfma_f32_16x16x32_bf16 v[96:99], v[100:103], v[194:197], v[96:99]
	v_mfma_f32_16x16x32_bf16 v[92:95], v[140:143], v[194:197], v[92:95]
	v_mfma_f32_16x16x32_bf16 v[76:79], v[100:103], v[202:205], v[76:79]
	v_mfma_f32_16x16x32_bf16 v[72:75], v[140:143], v[202:205], v[72:75]
	s_setprio 0
	s_setprio 1
	v_mfma_f32_16x16x32_bf16 v[128:131], v[144:147], v[174:177], v[128:131]
	v_mfma_f32_16x16x32_bf16 v[124:127], v[152:155], v[174:177], v[124:127]
	v_mfma_f32_16x16x32_bf16 v[108:111], v[144:147], v[182:185], v[108:111]
	v_mfma_f32_16x16x32_bf16 v[104:107], v[152:155], v[182:185], v[104:107]
	v_mfma_f32_16x16x32_bf16 v[88:91], v[144:147], v[190:193], v[88:91]
	v_mfma_f32_16x16x32_bf16 v[80:83], v[152:155], v[190:193], v[80:83]
	v_mfma_f32_16x16x32_bf16 v[68:71], v[144:147], v[198:201], v[68:71]
	v_mfma_f32_16x16x32_bf16 v[64:67], v[152:155], v[198:201], v[64:67]
	v_mfma_f32_16x16x32_bf16 v[128:131], v[148:151], v[178:181], v[128:131]
	v_mfma_f32_16x16x32_bf16 v[124:127], v[170:173], v[178:181], v[124:127]
	v_mfma_f32_16x16x32_bf16 v[108:111], v[148:151], v[186:189], v[108:111]
	v_mfma_f32_16x16x32_bf16 v[104:107], v[170:173], v[186:189], v[104:107]
	v_mfma_f32_16x16x32_bf16 v[88:91], v[148:151], v[194:197], v[88:91]
	v_mfma_f32_16x16x32_bf16 v[80:83], v[170:173], v[194:197], v[80:83]
	v_mfma_f32_16x16x32_bf16 v[68:71], v[148:151], v[202:205], v[68:71]
	v_mfma_f32_16x16x32_bf16 v[64:67], v[170:173], v[202:205], v[64:67]
	s_setprio 0
	s_barrier
	s_add_i32 s8, s61, s3
	v_lshl_add_u64 v[214:215], s[38:39], 0, v[156:157]
	s_mov_b32 m0, s8
	ds_read_b128 v[174:177], v210 offset:16384
	ds_read_b128 v[178:181], v210 offset:17408
	ds_read_b128 v[182:185], v210 offset:18432
	ds_read_b128 v[186:189], v210 offset:19456
	ds_read_b128 v[190:193], v210 offset:20480
	ds_read_b128 v[194:197], v210 offset:21504
	ds_read_b128 v[198:201], v210 offset:22528
	ds_read_b128 v[202:205], v210 offset:23552
	global_load_lds_dwordx4 v[214:215], off
	s_add_i32 m0, s8, 0x2000
	s_add_u32 s8, s38, 0x18000
	v_lshl_add_u64 v[216:217], s[38:39], 0, v[158:159]
	s_addc_u32 s9, s39, 0
	s_add_i32 s84, s62, s3
	global_load_lds_dwordx4 v[216:217], off
	v_lshl_add_u64 v[218:219], s[8:9], 0, v[156:157]
	s_mov_b32 m0, s84
	v_lshl_add_u64 v[220:221], s[40:41], 0, v[158:159]
	global_load_lds_dwordx4 v[218:219], off
	v_lshl_add_u64 v[218:219], s[8:9], 0, v[158:159]
	s_add_i32 m0, s84, 0x2000
	s_nop 0
	global_load_lds_dwordx4 v[218:219], off
	v_lshl_add_u64 v[218:219], s[40:41], 0, v[156:157]
	s_mov_b32 m0, s42
	s_nop 0
	global_load_lds_dwordx4 v[218:219], off
	s_mov_b32 m0, s43
	s_nop 0
	global_load_lds_dwordx4 v[220:221], off
	s_waitcnt vmcnt(8)
	s_waitcnt lgkmcnt(0)
	s_setprio 1
	s_barrier
	v_mfma_f32_16x16x32_bf16 v[60:63], v[84:87], v[174:177], v[60:63]
	v_mfma_f32_16x16x32_bf16 v[56:59], v[120:123], v[174:177], v[56:59]
	v_mfma_f32_16x16x32_bf16 v[44:47], v[84:87], v[182:185], v[44:47]
	v_mfma_f32_16x16x32_bf16 v[40:43], v[120:123], v[182:185], v[40:43]
	v_mfma_f32_16x16x32_bf16 v[28:31], v[84:87], v[190:193], v[28:31]
	v_mfma_f32_16x16x32_bf16 v[24:27], v[120:123], v[190:193], v[24:27]
	v_mfma_f32_16x16x32_bf16 v[12:15], v[84:87], v[198:201], v[12:15]
	v_mfma_f32_16x16x32_bf16 v[8:11], v[120:123], v[198:201], v[8:11]
	v_mfma_f32_16x16x32_bf16 v[60:63], v[100:103], v[178:181], v[60:63]
	v_mfma_f32_16x16x32_bf16 v[56:59], v[140:143], v[178:181], v[56:59]
	v_mfma_f32_16x16x32_bf16 v[44:47], v[100:103], v[186:189], v[44:47]
	v_mfma_f32_16x16x32_bf16 v[40:43], v[140:143], v[186:189], v[40:43]
	v_mfma_f32_16x16x32_bf16 v[28:31], v[100:103], v[194:197], v[28:31]
	v_mfma_f32_16x16x32_bf16 v[24:27], v[140:143], v[194:197], v[24:27]
	v_mfma_f32_16x16x32_bf16 v[12:15], v[100:103], v[202:205], v[12:15]
	v_mfma_f32_16x16x32_bf16 v[8:11], v[140:143], v[202:205], v[8:11]
	s_setprio 0
	s_setprio 1
	v_mfma_f32_16x16x32_bf16 v[52:55], v[144:147], v[174:177], v[52:55]
	v_mfma_f32_16x16x32_bf16 v[48:51], v[152:155], v[174:177], v[48:51]
	v_mfma_f32_16x16x32_bf16 v[36:39], v[144:147], v[182:185], v[36:39]
	v_mfma_f32_16x16x32_bf16 v[32:35], v[152:155], v[182:185], v[32:35]
	v_mfma_f32_16x16x32_bf16 v[20:23], v[144:147], v[190:193], v[20:23]
	v_mfma_f32_16x16x32_bf16 v[16:19], v[152:155], v[190:193], v[16:19]
	v_mfma_f32_16x16x32_bf16 v[4:7], v[144:147], v[198:201], v[4:7]
	v_mfma_f32_16x16x32_bf16 v[0:3], v[152:155], v[198:201], v[0:3]
	v_mfma_f32_16x16x32_bf16 v[52:55], v[148:151], v[178:181], v[52:55]
	v_mfma_f32_16x16x32_bf16 v[48:51], v[170:173], v[178:181], v[48:51]
	v_mfma_f32_16x16x32_bf16 v[36:39], v[148:151], v[186:189], v[36:39]
	v_mfma_f32_16x16x32_bf16 v[32:35], v[170:173], v[186:189], v[32:35]
	v_mfma_f32_16x16x32_bf16 v[20:23], v[148:151], v[194:197], v[20:23]
	v_mfma_f32_16x16x32_bf16 v[16:19], v[170:173], v[194:197], v[16:19]
	v_mfma_f32_16x16x32_bf16 v[4:7], v[148:151], v[202:205], v[4:7]
	v_mfma_f32_16x16x32_bf16 v[0:3], v[170:173], v[202:205], v[0:3]
	s_setprio 0
	s_barrier
	s_add_i32 s84, 0, 0x18000
	s_add_i32 s85, 0, 0x1c000
	v_add_u32_e32 v140, s84, v207
	v_add_u32_e32 v160, s85, v207
	ds_read_b128 v[84:87], v140
	ds_read_b128 v[100:103], v140 offset:1024
	ds_read_b128 v[120:123], v140 offset:2048
	ds_read_b128 v[140:143], v140 offset:3072
	ds_read_b128 v[144:147], v160
	ds_read_b128 v[148:151], v160 offset:1024
	ds_read_b128 v[152:155], v160 offset:2048
	ds_read_b128 v[170:173], v160 offset:3072
	s_add_u32 s8, s40, 0x18000
	s_addc_u32 s9, s41, 0
	s_mov_b32 m0, s44
	v_lshl_add_u64 v[222:223], s[8:9], 0, v[156:157]
	ds_read_b128 v[174:177], v210 offset:32768
	ds_read_b128 v[178:181], v210 offset:33792
	ds_read_b128 v[182:185], v210 offset:34816
	ds_read_b128 v[186:189], v210 offset:35840
	ds_read_b128 v[190:193], v210 offset:36864
	ds_read_b128 v[194:197], v210 offset:37888
	ds_read_b128 v[198:201], v210 offset:38912
	ds_read_b128 v[202:205], v210 offset:39936
	global_load_lds_dwordx4 v[222:223], off
	v_lshl_add_u64 v[222:223], s[8:9], 0, v[158:159]
	s_mov_b32 m0, s45
	s_nop 0
	global_load_lds_dwordx4 v[222:223], off
	s_waitcnt vmcnt(8)
	s_waitcnt lgkmcnt(0)
	s_setprio 1
	s_barrier
	v_mfma_f32_16x16x32_bf16 v[136:139], v[84:87], v[174:177], v[136:139]
	v_mfma_f32_16x16x32_bf16 v[132:135], v[120:123], v[174:177], v[132:135]
	v_mfma_f32_16x16x32_bf16 v[116:119], v[84:87], v[182:185], v[116:119]
	v_mfma_f32_16x16x32_bf16 v[112:115], v[120:123], v[182:185], v[112:115]
	v_mfma_f32_16x16x32_bf16 v[96:99], v[84:87], v[190:193], v[96:99]
	v_mfma_f32_16x16x32_bf16 v[92:95], v[120:123], v[190:193], v[92:95]
	v_mfma_f32_16x16x32_bf16 v[76:79], v[84:87], v[198:201], v[76:79]
	v_mfma_f32_16x16x32_bf16 v[72:75], v[120:123], v[198:201], v[72:75]
	v_mfma_f32_16x16x32_bf16 v[136:139], v[100:103], v[178:181], v[136:139]
	v_mfma_f32_16x16x32_bf16 v[132:135], v[140:143], v[178:181], v[132:135]
	v_mfma_f32_16x16x32_bf16 v[116:119], v[100:103], v[186:189], v[116:119]
	v_mfma_f32_16x16x32_bf16 v[112:115], v[140:143], v[186:189], v[112:115]
	v_mfma_f32_16x16x32_bf16 v[96:99], v[100:103], v[194:197], v[96:99]
	v_mfma_f32_16x16x32_bf16 v[92:95], v[140:143], v[194:197], v[92:95]
	v_mfma_f32_16x16x32_bf16 v[76:79], v[100:103], v[202:205], v[76:79]
	v_mfma_f32_16x16x32_bf16 v[72:75], v[140:143], v[202:205], v[72:75]
	s_setprio 0
	s_setprio 1
	v_mfma_f32_16x16x32_bf16 v[128:131], v[144:147], v[174:177], v[128:131]
	v_mfma_f32_16x16x32_bf16 v[124:127], v[152:155], v[174:177], v[124:127]
	v_mfma_f32_16x16x32_bf16 v[108:111], v[144:147], v[182:185], v[108:111]
	v_mfma_f32_16x16x32_bf16 v[104:107], v[152:155], v[182:185], v[104:107]
	v_mfma_f32_16x16x32_bf16 v[88:91], v[144:147], v[190:193], v[88:91]
	v_mfma_f32_16x16x32_bf16 v[80:83], v[152:155], v[190:193], v[80:83]
	v_mfma_f32_16x16x32_bf16 v[68:71], v[144:147], v[198:201], v[68:71]
	v_mfma_f32_16x16x32_bf16 v[64:67], v[152:155], v[198:201], v[64:67]
	v_mfma_f32_16x16x32_bf16 v[128:131], v[148:151], v[178:181], v[128:131]
	v_mfma_f32_16x16x32_bf16 v[124:127], v[170:173], v[178:181], v[124:127]
	v_mfma_f32_16x16x32_bf16 v[108:111], v[148:151], v[186:189], v[108:111]
	v_mfma_f32_16x16x32_bf16 v[104:107], v[170:173], v[186:189], v[104:107]
	v_mfma_f32_16x16x32_bf16 v[88:91], v[148:151], v[194:197], v[88:91]
	v_mfma_f32_16x16x32_bf16 v[80:83], v[170:173], v[194:197], v[80:83]
	v_mfma_f32_16x16x32_bf16 v[68:71], v[148:151], v[202:205], v[68:71]
	v_mfma_f32_16x16x32_bf16 v[64:67], v[170:173], v[202:205], v[64:67]
	s_setprio 0
	s_barrier
	s_add_i32 s8, s84, s3
	v_lshl_add_u64 v[214:215], v[214:215], 0, s[20:21]
	s_mov_b32 m0, s8
	ds_read_b128 v[174:177], v210 offset:49152
	ds_read_b128 v[178:181], v210 offset:50176
	ds_read_b128 v[182:185], v210 offset:51200
	ds_read_b128 v[186:189], v210 offset:52224
	ds_read_b128 v[190:193], v210 offset:53248
	ds_read_b128 v[194:197], v210 offset:54272
	ds_read_b128 v[198:201], v210 offset:55296
	ds_read_b128 v[202:205], v210 offset:56320
	global_load_lds_dwordx4 v[214:215], off
	s_add_i32 m0, s8, 0x2000
	s_add_u32 s8, s38, 0x18080
	v_lshl_add_u64 v[214:215], v[216:217], 0, s[20:21]
	s_addc_u32 s9, s39, 0
	s_add_i32 s38, s85, s3
	global_load_lds_dwordx4 v[214:215], off
	v_lshl_add_u64 v[214:215], s[8:9], 0, v[156:157]
	s_mov_b32 m0, s38
	s_nop 0
	global_load_lds_dwordx4 v[214:215], off
	v_lshl_add_u64 v[214:215], s[8:9], 0, v[158:159]
	s_add_i32 m0, s38, 0x2000
	s_nop 0
	global_load_lds_dwordx4 v[214:215], off
	v_lshl_add_u64 v[214:215], v[218:219], 0, s[20:21]
	s_mov_b32 m0, s51
	s_nop 0
	global_load_lds_dwordx4 v[214:215], off
	v_lshl_add_u64 v[214:215], v[220:221], 0, s[20:21]
	s_mov_b32 m0, s52
	s_nop 0
	global_load_lds_dwordx4 v[214:215], off
	s_waitcnt vmcnt(8)
	s_waitcnt lgkmcnt(0)
	s_setprio 1
	s_barrier
	v_mfma_f32_16x16x32_bf16 v[60:63], v[84:87], v[174:177], v[60:63]
	v_mfma_f32_16x16x32_bf16 v[56:59], v[120:123], v[174:177], v[56:59]
	v_mfma_f32_16x16x32_bf16 v[44:47], v[84:87], v[182:185], v[44:47]
	v_mfma_f32_16x16x32_bf16 v[40:43], v[120:123], v[182:185], v[40:43]
	v_mfma_f32_16x16x32_bf16 v[28:31], v[84:87], v[190:193], v[28:31]
	v_mfma_f32_16x16x32_bf16 v[24:27], v[120:123], v[190:193], v[24:27]
	v_mfma_f32_16x16x32_bf16 v[12:15], v[84:87], v[198:201], v[12:15]
	v_mfma_f32_16x16x32_bf16 v[8:11], v[120:123], v[198:201], v[8:11]
	v_mfma_f32_16x16x32_bf16 v[60:63], v[100:103], v[178:181], v[60:63]
	v_mfma_f32_16x16x32_bf16 v[56:59], v[140:143], v[178:181], v[56:59]
	v_mfma_f32_16x16x32_bf16 v[44:47], v[100:103], v[186:189], v[44:47]
	v_mfma_f32_16x16x32_bf16 v[40:43], v[140:143], v[186:189], v[40:43]
	v_mfma_f32_16x16x32_bf16 v[28:31], v[100:103], v[194:197], v[28:31]
	v_mfma_f32_16x16x32_bf16 v[24:27], v[140:143], v[194:197], v[24:27]
	v_mfma_f32_16x16x32_bf16 v[12:15], v[100:103], v[202:205], v[12:15]
	v_mfma_f32_16x16x32_bf16 v[8:11], v[140:143], v[202:205], v[8:11]
	s_setprio 0
	s_setprio 1
	v_mfma_f32_16x16x32_bf16 v[52:55], v[144:147], v[174:177], v[52:55]
	v_mfma_f32_16x16x32_bf16 v[48:51], v[152:155], v[174:177], v[48:51]
	v_mfma_f32_16x16x32_bf16 v[36:39], v[144:147], v[182:185], v[36:39]
	v_mfma_f32_16x16x32_bf16 v[32:35], v[152:155], v[182:185], v[32:35]
	v_mfma_f32_16x16x32_bf16 v[20:23], v[144:147], v[190:193], v[20:23]
	v_mfma_f32_16x16x32_bf16 v[16:19], v[152:155], v[190:193], v[16:19]
	v_mfma_f32_16x16x32_bf16 v[4:7], v[144:147], v[198:201], v[4:7]
	v_mfma_f32_16x16x32_bf16 v[0:3], v[152:155], v[198:201], v[0:3]
	v_mfma_f32_16x16x32_bf16 v[52:55], v[148:151], v[178:181], v[52:55]
	v_mfma_f32_16x16x32_bf16 v[48:51], v[170:173], v[178:181], v[48:51]
	v_mfma_f32_16x16x32_bf16 v[36:39], v[148:151], v[186:189], v[36:39]
	v_mfma_f32_16x16x32_bf16 v[32:35], v[170:173], v[186:189], v[32:35]
	v_mfma_f32_16x16x32_bf16 v[20:23], v[148:151], v[194:197], v[20:23]
	v_mfma_f32_16x16x32_bf16 v[16:19], v[170:173], v[194:197], v[16:19]
	v_mfma_f32_16x16x32_bf16 v[4:7], v[148:151], v[202:205], v[4:7]
	v_mfma_f32_16x16x32_bf16 v[0:3], v[170:173], v[202:205], v[0:3]
	s_setprio 0
	s_barrier
	s_add_i32 s83, s83, 2
	s_add_u32 s81, s81, 0x100
	s_addc_u32 s82, s82, 0
	s_cmp_gt_u32 s83, 3
	s_mov_b64 s[8:9], s[6:7]
	s_cbranch_scc0 .LBB0_771
	s_and_b64 vcc, exec, s[30:31]
	s_cbranch_vccz .LBB0_774
	s_barrier

.LBB0_938:
	ds_read_b128 v[128:131], v175
	ds_read_b128 v[132:135], v175 offset:1024
	ds_read_b128 v[136:139], v175 offset:2048
	ds_read_b128 v[140:143], v175 offset:3072
	ds_read_b128 v[144:147], v176
	ds_read_b128 v[148:151], v176 offset:1024
	ds_read_b128 v[168:171], v176 offset:2048
	ds_read_b128 v[182:185], v176 offset:3072
	s_add_u32 s36, s6, 0xfffe0080
	s_addc_u32 s37, s7, -1
	s_cmp_eq_u32 s42, 4
	s_cselect_b32 s39, s9, s37
	s_cselect_b32 s38, s27, s36
	s_cselect_b32 s37, s23, s41
	s_cselect_b32 s36, s35, s40
	v_lshl_add_u64 v[218:219], s[6:7], 0, v[158:159]
	s_add_i32 m0, s48, 0xc000
	ds_read_b128 v[186:189], v177
	ds_read_b128 v[190:193], v177 offset:1024
	ds_read_b128 v[194:197], v177 offset:2048
	ds_read_b128 v[198:201], v177 offset:3072
	ds_read_b128 v[202:205], v177 offset:4096
	ds_read_b128 v[206:209], v177 offset:5120
	ds_read_b128 v[210:213], v177 offset:6144
	ds_read_b128 v[214:217], v177 offset:7168
	global_load_lds_dwordx4 v[218:219], off
	v_lshl_add_u64 v[218:219], s[6:7], 0, v[160:161]
	s_add_i32 m0, s48, 0xe000
	s_nop 0
	global_load_lds_dwordx4 v[218:219], off
	s_waitcnt vmcnt(8)
	s_waitcnt lgkmcnt(0)
	s_setprio 1
	s_barrier
	v_mfma_f32_16x16x32_bf16 v[124:127], v[128:131], v[186:189], v[124:127]
	v_mfma_f32_16x16x32_bf16 v[120:123], v[136:139], v[186:189], v[120:123]
	v_mfma_f32_16x16x32_bf16 v[112:115], v[128:131], v[194:197], v[112:115]
	v_mfma_f32_16x16x32_bf16 v[116:119], v[136:139], v[194:197], v[116:119]
	v_mfma_f32_16x16x32_bf16 v[96:99], v[128:131], v[202:205], v[96:99]
	v_mfma_f32_16x16x32_bf16 v[104:107], v[136:139], v[202:205], v[104:107]
	v_mfma_f32_16x16x32_bf16 v[76:79], v[128:131], v[210:213], v[76:79]
	v_mfma_f32_16x16x32_bf16 v[72:75], v[136:139], v[210:213], v[72:75]
	v_mfma_f32_16x16x32_bf16 v[124:127], v[132:135], v[190:193], v[124:127]
	v_mfma_f32_16x16x32_bf16 v[120:123], v[140:143], v[190:193], v[120:123]
	v_mfma_f32_16x16x32_bf16 v[112:115], v[132:135], v[198:201], v[112:115]
	v_mfma_f32_16x16x32_bf16 v[116:119], v[140:143], v[198:201], v[116:119]
	v_mfma_f32_16x16x32_bf16 v[96:99], v[132:135], v[206:209], v[96:99]
	v_mfma_f32_16x16x32_bf16 v[104:107], v[140:143], v[206:209], v[104:107]
	v_mfma_f32_16x16x32_bf16 v[76:79], v[132:135], v[214:217], v[76:79]
	v_mfma_f32_16x16x32_bf16 v[72:75], v[140:143], v[214:217], v[72:75]
	s_setprio 0
	s_setprio 1
	v_mfma_f32_16x16x32_bf16 v[108:111], v[144:147], v[186:189], v[108:111]
	v_mfma_f32_16x16x32_bf16 v[100:103], v[168:171], v[186:189], v[100:103]
	v_mfma_f32_16x16x32_bf16 v[88:91], v[144:147], v[194:197], v[88:91]
	v_mfma_f32_16x16x32_bf16 v[92:95], v[168:171], v[194:197], v[92:95]
	v_mfma_f32_16x16x32_bf16 v[84:87], v[144:147], v[202:205], v[84:87]
	v_mfma_f32_16x16x32_bf16 v[80:83], v[168:171], v[202:205], v[80:83]
	v_mfma_f32_16x16x32_bf16 v[68:71], v[144:147], v[210:213], v[68:71]
	v_mfma_f32_16x16x32_bf16 v[64:67], v[168:171], v[210:213], v[64:67]
	v_mfma_f32_16x16x32_bf16 v[108:111], v[148:151], v[190:193], v[108:111]
	v_mfma_f32_16x16x32_bf16 v[100:103], v[182:185], v[190:193], v[100:103]
	v_mfma_f32_16x16x32_bf16 v[88:91], v[148:151], v[198:201], v[88:91]
	v_mfma_f32_16x16x32_bf16 v[92:95], v[182:185], v[198:201], v[92:95]
	v_mfma_f32_16x16x32_bf16 v[84:87], v[148:151], v[206:209], v[84:87]
	v_mfma_f32_16x16x32_bf16 v[80:83], v[182:185], v[206:209], v[80:83]
	v_mfma_f32_16x16x32_bf16 v[68:71], v[148:151], v[214:217], v[68:71]
	v_mfma_f32_16x16x32_bf16 v[64:67], v[182:185], v[214:217], v[64:67]
	s_setprio 0
	s_barrier
	s_add_i32 s43, s72, s47
	v_lshl_add_u64 v[218:219], s[36:37], 0, v[152:153]
	s_mov_b32 m0, s43
	ds_read_b128 v[186:189], v177 offset:16384
	ds_read_b128 v[190:193], v177 offset:17408
	ds_read_b128 v[194:197], v177 offset:18432
	ds_read_b128 v[198:201], v177 offset:19456
	ds_read_b128 v[202:205], v177 offset:20480
	ds_read_b128 v[206:209], v177 offset:21504
	ds_read_b128 v[210:213], v177 offset:22528
	ds_read_b128 v[214:217], v177 offset:23552
	global_load_lds_dwordx4 v[218:219], off
	s_add_i32 m0, s43, 0x2000
	s_add_u32 s88, s36, 0x20000
	v_lshl_add_u64 v[220:221], s[36:37], 0, v[154:155]
	s_addc_u32 s89, s37, 0
	s_add_i32 s43, s73, s47
	global_load_lds_dwordx4 v[220:221], off
	v_lshl_add_u64 v[222:223], s[88:89], 0, v[152:153]
	s_mov_b32 m0, s43
	v_lshl_add_u64 v[224:225], s[38:39], 0, v[154:155]
	global_load_lds_dwordx4 v[222:223], off
	v_lshl_add_u64 v[222:223], s[88:89], 0, v[154:155]
	s_add_i32 m0, s43, 0x2000
	s_nop 0
	global_load_lds_dwordx4 v[222:223], off
	v_lshl_add_u64 v[222:223], s[38:39], 0, v[152:153]
	s_mov_b32 m0, s48
	s_nop 0
	global_load_lds_dwordx4 v[222:223], off
	s_mov_b32 m0, s49
	s_nop 0
	global_load_lds_dwordx4 v[224:225], off
	s_waitcnt vmcnt(8)
	s_waitcnt lgkmcnt(0)
	s_setprio 1
	s_barrier
	v_mfma_f32_16x16x32_bf16 v[60:63], v[128:131], v[186:189], v[60:63]
	v_mfma_f32_16x16x32_bf16 v[56:59], v[136:139], v[186:189], v[56:59]
	v_mfma_f32_16x16x32_bf16 v[44:47], v[128:131], v[194:197], v[44:47]
	v_mfma_f32_16x16x32_bf16 v[40:43], v[136:139], v[194:197], v[40:43]
	v_mfma_f32_16x16x32_bf16 v[28:31], v[128:131], v[202:205], v[28:31]
	v_mfma_f32_16x16x32_bf16 v[24:27], v[136:139], v[202:205], v[24:27]
	v_mfma_f32_16x16x32_bf16 v[12:15], v[128:131], v[210:213], v[12:15]
	v_mfma_f32_16x16x32_bf16 v[8:11], v[136:139], v[210:213], v[8:11]
	v_mfma_f32_16x16x32_bf16 v[60:63], v[132:135], v[190:193], v[60:63]
	v_mfma_f32_16x16x32_bf16 v[56:59], v[140:143], v[190:193], v[56:59]
	v_mfma_f32_16x16x32_bf16 v[44:47], v[132:135], v[198:201], v[44:47]
	v_mfma_f32_16x16x32_bf16 v[40:43], v[140:143], v[198:201], v[40:43]
	v_mfma_f32_16x16x32_bf16 v[28:31], v[132:135], v[206:209], v[28:31]
	v_mfma_f32_16x16x32_bf16 v[24:27], v[140:143], v[206:209], v[24:27]
	v_mfma_f32_16x16x32_bf16 v[12:15], v[132:135], v[214:217], v[12:15]
	v_mfma_f32_16x16x32_bf16 v[8:11], v[140:143], v[214:217], v[8:11]
	s_setprio 0
	s_setprio 1
	v_mfma_f32_16x16x32_bf16 v[52:55], v[144:147], v[186:189], v[52:55]
	v_mfma_f32_16x16x32_bf16 v[48:51], v[168:171], v[186:189], v[48:51]
	v_mfma_f32_16x16x32_bf16 v[36:39], v[144:147], v[194:197], v[36:39]
	v_mfma_f32_16x16x32_bf16 v[32:35], v[168:171], v[194:197], v[32:35]
	v_mfma_f32_16x16x32_bf16 v[20:23], v[144:147], v[202:205], v[20:23]
	v_mfma_f32_16x16x32_bf16 v[16:19], v[168:171], v[202:205], v[16:19]
	v_mfma_f32_16x16x32_bf16 v[4:7], v[144:147], v[210:213], v[4:7]
	v_mfma_f32_16x16x32_bf16 v[0:3], v[168:171], v[210:213], v[0:3]
	v_mfma_f32_16x16x32_bf16 v[52:55], v[148:151], v[190:193], v[52:55]
	v_mfma_f32_16x16x32_bf16 v[48:51], v[182:185], v[190:193], v[48:51]
	v_mfma_f32_16x16x32_bf16 v[36:39], v[148:151], v[198:201], v[36:39]
	v_mfma_f32_16x16x32_bf16 v[32:35], v[182:185], v[198:201], v[32:35]
	v_mfma_f32_16x16x32_bf16 v[20:23], v[148:151], v[206:209], v[20:23]
	v_mfma_f32_16x16x32_bf16 v[16:19], v[182:185], v[206:209], v[16:19]
	v_mfma_f32_16x16x32_bf16 v[4:7], v[148:151], v[214:217], v[4:7]
	v_mfma_f32_16x16x32_bf16 v[0:3], v[182:185], v[214:217], v[0:3]
	s_setprio 0
	s_barrier
	s_add_i32 s43, 0, 0x18000
	s_add_i32 s88, 0, 0x1c000
	v_add_u32_e32 v140, s43, v173
	v_add_u32_e32 v156, s88, v173
	ds_read_b128 v[128:131], v140
	ds_read_b128 v[132:135], v140 offset:1024
	ds_read_b128 v[136:139], v140 offset:2048
	ds_read_b128 v[140:143], v140 offset:3072
	ds_read_b128 v[144:147], v156
	ds_read_b128 v[148:151], v156 offset:1024
	ds_read_b128 v[168:171], v156 offset:2048
	ds_read_b128 v[182:185], v156 offset:3072
	s_add_u32 s38, s38, 0x20000
	s_addc_u32 s39, s39, 0
	s_mov_b32 m0, s50
	v_lshl_add_u64 v[226:227], s[38:39], 0, v[152:153]
	ds_read_b128 v[186:189], v177 offset:32768
	ds_read_b128 v[190:193], v177 offset:33792
	ds_read_b128 v[194:197], v177 offset:34816
	ds_read_b128 v[198:201], v177 offset:35840
	ds_read_b128 v[202:205], v177 offset:36864
	ds_read_b128 v[206:209], v177 offset:37888
	ds_read_b128 v[210:213], v177 offset:38912
	ds_read_b128 v[214:217], v177 offset:39936
	global_load_lds_dwordx4 v[226:227], off
	v_lshl_add_u64 v[226:227], s[38:39], 0, v[154:155]
	s_mov_b32 m0, s51
	s_nop 0
	global_load_lds_dwordx4 v[226:227], off
	s_waitcnt vmcnt(8)
	s_waitcnt lgkmcnt(0)
	s_setprio 1
	s_barrier
	v_mfma_f32_16x16x32_bf16 v[124:127], v[128:131], v[186:189], v[124:127]
	v_mfma_f32_16x16x32_bf16 v[120:123], v[136:139], v[186:189], v[120:123]
	v_mfma_f32_16x16x32_bf16 v[112:115], v[128:131], v[194:197], v[112:115]
	v_mfma_f32_16x16x32_bf16 v[116:119], v[136:139], v[194:197], v[116:119]
	v_mfma_f32_16x16x32_bf16 v[96:99], v[128:131], v[202:205], v[96:99]
	v_mfma_f32_16x16x32_bf16 v[104:107], v[136:139], v[202:205], v[104:107]
	v_mfma_f32_16x16x32_bf16 v[76:79], v[128:131], v[210:213], v[76:79]
	v_mfma_f32_16x16x32_bf16 v[72:75], v[136:139], v[210:213], v[72:75]
	v_mfma_f32_16x16x32_bf16 v[124:127], v[132:135], v[190:193], v[124:127]
	v_mfma_f32_16x16x32_bf16 v[120:123], v[140:143], v[190:193], v[120:123]
	v_mfma_f32_16x16x32_bf16 v[112:115], v[132:135], v[198:201], v[112:115]
	v_mfma_f32_16x16x32_bf16 v[116:119], v[140:143], v[198:201], v[116:119]
	v_mfma_f32_16x16x32_bf16 v[96:99], v[132:135], v[206:209], v[96:99]
	v_mfma_f32_16x16x32_bf16 v[104:107], v[140:143], v[206:209], v[104:107]
	v_mfma_f32_16x16x32_bf16 v[76:79], v[132:135], v[214:217], v[76:79]
	v_mfma_f32_16x16x32_bf16 v[72:75], v[140:143], v[214:217], v[72:75]
	s_setprio 0
	s_setprio 1
	v_mfma_f32_16x16x32_bf16 v[108:111], v[144:147], v[186:189], v[108:111]
	v_mfma_f32_16x16x32_bf16 v[100:103], v[168:171], v[186:189], v[100:103]
	v_mfma_f32_16x16x32_bf16 v[88:91], v[144:147], v[194:197], v[88:91]
	v_mfma_f32_16x16x32_bf16 v[92:95], v[168:171], v[194:197], v[92:95]
	v_mfma_f32_16x16x32_bf16 v[84:87], v[144:147], v[202:205], v[84:87]
	v_mfma_f32_16x16x32_bf16 v[80:83], v[168:171], v[202:205], v[80:83]
	v_mfma_f32_16x16x32_bf16 v[68:71], v[144:147], v[210:213], v[68:71]
	v_mfma_f32_16x16x32_bf16 v[64:67], v[168:171], v[210:213], v[64:67]
	v_mfma_f32_16x16x32_bf16 v[108:111], v[148:151], v[190:193], v[108:111]
	v_mfma_f32_16x16x32_bf16 v[100:103], v[182:185], v[190:193], v[100:103]
	v_mfma_f32_16x16x32_bf16 v[88:91], v[148:151], v[198:201], v[88:91]
	v_mfma_f32_16x16x32_bf16 v[92:95], v[182:185], v[198:201], v[92:95]
	v_mfma_f32_16x16x32_bf16 v[84:87], v[148:151], v[206:209], v[84:87]
	v_mfma_f32_16x16x32_bf16 v[80:83], v[182:185], v[206:209], v[80:83]
	v_mfma_f32_16x16x32_bf16 v[68:71], v[148:151], v[214:217], v[68:71]
	v_mfma_f32_16x16x32_bf16 v[64:67], v[182:185], v[214:217], v[64:67]
	s_setprio 0
	s_barrier
	s_add_i32 s38, s43, s47
	v_lshl_add_u64 v[218:219], v[218:219], 0, s[16:17]
	s_mov_b32 m0, s38
	ds_read_b128 v[186:189], v177 offset:49152
	ds_read_b128 v[190:193], v177 offset:50176
	ds_read_b128 v[194:197], v177 offset:51200
	ds_read_b128 v[198:201], v177 offset:52224
	ds_read_b128 v[202:205], v177 offset:53248
	ds_read_b128 v[206:209], v177 offset:54272
	ds_read_b128 v[210:213], v177 offset:55296
	ds_read_b128 v[214:217], v177 offset:56320
	global_load_lds_dwordx4 v[218:219], off
	s_add_i32 m0, s38, 0x2000
	s_add_u32 s36, s36, 0x20080
	v_lshl_add_u64 v[218:219], v[220:221], 0, s[16:17]
	s_addc_u32 s37, s37, 0
	s_add_i32 s38, s88, s47
	global_load_lds_dwordx4 v[218:219], off
	v_lshl_add_u64 v[218:219], s[36:37], 0, v[152:153]
	s_mov_b32 m0, s38
	s_nop 0
	global_load_lds_dwordx4 v[218:219], off
	v_lshl_add_u64 v[218:219], s[36:37], 0, v[154:155]
	s_add_i32 m0, s38, 0x2000
	s_nop 0
	global_load_lds_dwordx4 v[218:219], off
	v_lshl_add_u64 v[218:219], v[222:223], 0, s[16:17]
	s_mov_b32 m0, s61
	s_nop 0
	global_load_lds_dwordx4 v[218:219], off
	v_lshl_add_u64 v[218:219], v[224:225], 0, s[16:17]
	s_mov_b32 m0, s62
	s_nop 0
	global_load_lds_dwordx4 v[218:219], off
	s_waitcnt vmcnt(8)
	s_waitcnt lgkmcnt(0)
	s_setprio 1
	s_barrier
	v_mfma_f32_16x16x32_bf16 v[60:63], v[128:131], v[186:189], v[60:63]
	v_mfma_f32_16x16x32_bf16 v[56:59], v[136:139], v[186:189], v[56:59]
	v_mfma_f32_16x16x32_bf16 v[44:47], v[128:131], v[194:197], v[44:47]
	v_mfma_f32_16x16x32_bf16 v[40:43], v[136:139], v[194:197], v[40:43]
	v_mfma_f32_16x16x32_bf16 v[28:31], v[128:131], v[202:205], v[28:31]
	v_mfma_f32_16x16x32_bf16 v[24:27], v[136:139], v[202:205], v[24:27]
	v_mfma_f32_16x16x32_bf16 v[12:15], v[128:131], v[210:213], v[12:15]
	v_mfma_f32_16x16x32_bf16 v[8:11], v[136:139], v[210:213], v[8:11]
	v_mfma_f32_16x16x32_bf16 v[60:63], v[132:135], v[190:193], v[60:63]
	v_mfma_f32_16x16x32_bf16 v[56:59], v[140:143], v[190:193], v[56:59]
	v_mfma_f32_16x16x32_bf16 v[44:47], v[132:135], v[198:201], v[44:47]
	v_mfma_f32_16x16x32_bf16 v[40:43], v[140:143], v[198:201], v[40:43]
	v_mfma_f32_16x16x32_bf16 v[28:31], v[132:135], v[206:209], v[28:31]
	v_mfma_f32_16x16x32_bf16 v[24:27], v[140:143], v[206:209], v[24:27]
	v_mfma_f32_16x16x32_bf16 v[12:15], v[132:135], v[214:217], v[12:15]
	v_mfma_f32_16x16x32_bf16 v[8:11], v[140:143], v[214:217], v[8:11]
	s_setprio 0
	s_setprio 1
	v_mfma_f32_16x16x32_bf16 v[52:55], v[144:147], v[186:189], v[52:55]
	v_mfma_f32_16x16x32_bf16 v[48:51], v[168:171], v[186:189], v[48:51]
	v_mfma_f32_16x16x32_bf16 v[36:39], v[144:147], v[194:197], v[36:39]
	v_mfma_f32_16x16x32_bf16 v[32:35], v[168:171], v[194:197], v[32:35]
	v_mfma_f32_16x16x32_bf16 v[20:23], v[144:147], v[202:205], v[20:23]
	v_mfma_f32_16x16x32_bf16 v[16:19], v[168:171], v[202:205], v[16:19]
	v_mfma_f32_16x16x32_bf16 v[4:7], v[144:147], v[210:213], v[4:7]
	v_mfma_f32_16x16x32_bf16 v[0:3], v[168:171], v[210:213], v[0:3]
	v_mfma_f32_16x16x32_bf16 v[52:55], v[148:151], v[190:193], v[52:55]
	v_mfma_f32_16x16x32_bf16 v[48:51], v[182:185], v[190:193], v[48:51]
	v_mfma_f32_16x16x32_bf16 v[36:39], v[148:151], v[198:201], v[36:39]
	v_mfma_f32_16x16x32_bf16 v[32:35], v[182:185], v[198:201], v[32:35]
	v_mfma_f32_16x16x32_bf16 v[20:23], v[148:151], v[206:209], v[20:23]
	v_mfma_f32_16x16x32_bf16 v[16:19], v[182:185], v[206:209], v[16:19]
	v_mfma_f32_16x16x32_bf16 v[4:7], v[148:151], v[214:217], v[4:7]
	v_mfma_f32_16x16x32_bf16 v[0:3], v[182:185], v[214:217], v[0:3]
	s_setprio 0
	s_barrier
	s_add_i32 s42, s42, 2
	s_add_u32 s6, s6, 0x100
	s_addc_u32 s7, s7, 0
	s_add_u32 s40, s40, 0x100
	s_addc_u32 s41, s41, 0
	s_cmp_gt_u32 s42, 5
	s_cbranch_scc0 .LBB0_938
	s_and_b64 vcc, exec, s[18:19]
	s_cbranch_vccz .LBB0_941
	s_barrier
